# SSM scans with independent accumulation chains and scalar FMAs; SSMB outputs transposed through LDS for 16-byte stores; SSMB loop no longer waits on its own store
# speedup vs baseline: 1.0590x; 1.0076x over previous
; template <bool FULL>
; DI void ssm_item(const P& p, int l, int item, char* smem) {
;     ...
;   if (FULL) {
;     const float2* Ep = p.E + ((size_t)(b * 32 + g) * 64) * 64 + lane;
;     for (int cc = 0; cc < c; ++cc) {
;       const float2 e = Ep[cc * 64];
;       const float nhr = a4.z * hr - a4.w * hi + e.x, nhi = a4.z * hi + a4.w * hr + e.y;
;       hr = nhr; hi = nhi;
;     }
;     const float* cp = (quad < 2 ? p.c_re : p.c_im) + ((size_t)lg * 16 + ch) * 64 + (quad & 1) * 32;
;     const float sgn = quad < 2 ? 1.f : -1.f;
; #pragma unroll
;     for (int i = 0; i < 8; ++i) { const float4 t = ((const float4*)cp)[i]; creg[4 * i] = sgn * t.x; creg[4 * i + 1] = sgn * t.y; creg[4 * i + 2] = sgn * t.z; creg[4 * i + 3] = sgn * t.w; }
;     dsk = p.d_skip[l * 512 + g * 16 + ch];
;   }
;   const size_t tok0 = (size_t)b * SEQ + c * 128;
;   const int tt = lane >> 2, part = lane & 3;
;   uint2 raw = *(const uint2*)(p.u_ssm + (tok0 + tt) * 512 + g * 16 + part * 4);
; #pragma unroll 1
;   for (int s = 0; s < 8; ++s) {
;     float4 uf;
;     uf.x = __uint_as_float(raw.x << 16); uf.y = __uint_as_float(raw.x & 0xffff0000u);
;     uf.z = __uint_as_float(raw.y << 16); uf.w = __uint_as_float(raw.y & 0xffff0000u);
;     __builtin_amdgcn_wave_barrier();
;     *(float4*)(us + tt * 16 + part * 4) = uf;
;     __builtin_amdgcn_wave_barrier();
;     if (s + 1 < 8) raw = *(const uint2*)(p.u_ssm + (tok0 + (s + 1) * 16 + tt) * 512 + g * 16 + part * 4);
.LBB0_169:
	v_readlane_b32 s4, v251, 16
	v_readlane_b32 s9, v251, 21
	v_readlane_b32 s11, v251, 23
	v_cmp_gt_u32_e32 vcc, 32, v86
	v_readlane_b32 s8, v251, 20
	v_readlane_b32 s10, v251, 22
	s_waitcnt vmcnt(4)
	v_mov_b32_e32 v18, s11
	v_mov_b32_e32 v19, s9
	v_cndmask_b32_e32 v19, v18, v19, vcc
	v_mov_b32_e32 v18, s10
	v_mov_b32_e32 v43, s8
	v_and_b32_e32 v44, 15, v45
	v_cndmask_b32_e32 v18, v18, v43, vcc
	v_lshlrev_b64 v[38:39], 12, v[38:39]
	v_lshl_add_u64 v[18:19], v[18:19], 0, v[38:39]
	v_lshlrev_b32_e32 v192, 8, v44
	v_lshlrev_b32_e32 v38, 3, v86
	v_lshl_add_u64 v[18:19], v[18:19], 0, v[192:193]
	v_and_b32_e32 v192, 0x80, v38
	v_lshl_add_u64 v[18:19], v[18:19], 0, v[192:193]
	global_load_dwordx4 v[60:63], v[18:19], off offset:48
	global_load_dwordx4 v[56:59], v[18:19], off offset:32
	global_load_dwordx4 v[52:55], v[18:19], off offset:16
	global_load_dwordx4 v[48:51], v[18:19], off
	global_load_dwordx4 v[80:83], v[18:19], off offset:112
	global_load_dwordx4 v[72:75], v[18:19], off offset:96
	global_load_dwordx4 v[68:71], v[18:19], off offset:80
	global_load_dwordx4 v[64:67], v[18:19], off offset:64
	v_readlane_b32 s5, v251, 17
	v_lshlrev_b32_e32 v38, 4, v79
	v_readlane_b32 s4, v249, 29
	s_movk_i32 s1, 0x2500
	v_mul_lo_u32 v46, v46, s1
	v_add_u32_e32 v18, s4, v38
	v_readlane_b32 s6, v251, 18
	v_or_b32_e32 v18, v18, v44
	s_ashr_i32 s1, s0, 31
	v_cndmask_b32_e64 v42, -1.0, 1.0, vcc
	v_readlane_b32 s12, v251, 24
	v_readlane_b32 s13, v251, 25
	v_ashrrev_i32_e32 v19, 31, v18
	s_lshl_b64 s[0:1], s[0:1], 13
	s_lshl_b32 s6, s28, 7
	v_lshl_add_u64 v[18:19], v[18:19], 2, s[12:13]
	s_or_b32 s0, s0, s6
	global_load_dword v79, v[18:19], off
	v_mov_b32_e32 v19, s1
	v_ashrrev_i32_e32 v39, 31, v38
	v_lshlrev_b32_e32 v45, 2, v45
	v_and_b32_e32 v45, 12, v45
	v_lshlrev_b32_e32 v192, 1, v45
	v_add_u32_e32 v41, 0, v46
	v_lshrrev_b32_e32 v40, 4, v86
	v_lshlrev_b32_e32 v45, 2, v45
	s_movk_i32 s6, 0xfdf4
	v_lshlrev_b32_e32 v87, 8, v40
	v_readlane_b32 s7, v251, 19
	s_mov_b32 s7, 0
	v_readlane_b32 s14, v251, 26
	v_readlane_b32 s15, v251, 27
	v_readlane_b32 s16, v251, 28
	v_readlane_b32 s17, v251, 29
	v_readlane_b32 s18, v251, 30
	v_readlane_b32 s19, v251, 31
	v_readlane_b32 s5, v249, 30
	s_waitcnt vmcnt(4)
	v_mul_f32_e32 v77, v42, v82
	v_lshrrev_b32_e32 v82, 2, v86
	v_or_b32_e32 v18, s0, v82
	v_mul_f32_e32 v47, v42, v48
	v_mul_f32_e32 v48, v42, v49
	v_mul_f32_e32 v49, v42, v50
	v_mul_f32_e32 v50, v42, v51
	v_mul_f32_e32 v51, v42, v52
	v_mul_f32_e32 v52, v42, v53
	v_mul_f32_e32 v53, v42, v54
	v_mul_f32_e32 v54, v42, v55
	v_mul_f32_e32 v55, v42, v56
	v_mul_f32_e32 v56, v42, v57
	v_mul_f32_e32 v57, v42, v58
	v_mul_f32_e32 v58, v42, v59
	v_mul_f32_e32 v59, v42, v60
	v_mul_f32_e32 v60, v42, v61
	v_mul_f32_e32 v61, v42, v62
	v_mul_f32_e32 v62, v42, v63
	s_waitcnt vmcnt(1)
	v_mul_f32_e32 v63, v42, v64
	v_mul_f32_e32 v64, v42, v65
	v_mul_f32_e32 v65, v42, v66
	v_mul_f32_e32 v66, v42, v67
	v_mul_f32_e32 v67, v42, v68
	v_mul_f32_e32 v68, v42, v69
	v_mul_f32_e32 v69, v42, v70
	v_mul_f32_e32 v70, v42, v71
	v_mul_f32_e32 v71, v42, v72
	v_mul_f32_e32 v72, v42, v73
	v_mul_f32_e32 v73, v42, v74
	v_mul_f32_e32 v74, v42, v75
	v_mul_f32_e32 v75, v42, v80
	v_mul_f32_e32 v76, v42, v81
	v_mul_f32_e32 v78, v42, v83
	v_lshlrev_b64 v[42:43], 10, v[18:19]
	v_lshl_add_u64 v[80:81], s[94:95], 0, v[42:43]
	v_lshlrev_b64 v[42:43], 1, v[38:39]
	v_lshl_add_u64 v[38:39], v[80:81], 0, v[42:43]
	v_lshl_add_u64 v[38:39], v[38:39], 0, v[192:193]
	global_load_dwordx2 v[38:39], v[38:39], off
	v_lshlrev_b32_e32 v80, 6, v82
	v_add3_u32 v80, v41, v80, v45
	v_mad_u32_u24 v41, v44, s3, v41
	v_lshlrev_b32_e32 v82, 2, v40
	v_lshl_add_u32 v81, v40, 7, v41
	v_mad_i32_i24 v90, v44, s6, v41
	v_or_b32_e32 v83, 1, v82
	v_or_b32_e32 v84, 2, v82
	v_or_b32_e32 v85, 3, v82
	v_lshl_add_u64 v[40:41], s[94:95], 0, v[42:43]
	v_lshlrev_b32_e32 v88, 6, v83
	v_lshlrev_b32_e32 v89, 6, v84
	v_lshlrev_b32_e32 v91, 6, v85
	v_lshl_add_u64 v[40:41], v[40:41], 0, v[192:193]
	v_lshl_add_u64 v[42:43], s[86:87], 0, v[42:43]
	v_lshlrev_b32_e32 v192, 1, v44
	v_lshl_add_u64 v[42:43], v[42:43], 0, v[192:193]
	v_pk_mov_b32 v[44:45], v[16:17], v[16:17] op_sel:[1,0]
	v_lshl_add_u32 v86, v86, 2, 0
	v_add_u32_e32 v87, v90, v87
	v_add_u32_e32 v88, v90, v88
	v_add_u32_e32 v89, v90, v89
	v_add_u32_e32 v90, v90, v91
	s_waitcnt vmcnt(0)
	s_add_i32 s6, s7, 1
	s_branch .Lssmb_in
.LBB0_170:
	s_add_i32 s6, s7, 1
	s_waitcnt vmcnt(1)
.Lssmb_in:
	v_lshlrev_b32_e32 v92, 16, v38
	v_and_b32_e32 v93, 0xffff0000, v38
	v_lshlrev_b32_e32 v94, 16, v39
	v_and_b32_e32 v95, 0xffff0000, v39
	s_cmp_eq_u32 s7, 7
	ds_write_b128 v80, v[92:95] offset:8448
	s_cbranch_scc1 .LBB0_172
	s_lshl_b32 s60, s6, 4
	v_lshl_add_u64 v[38:39], v[18:19], 0, s[60:61]
	v_lshlrev_b64 v[38:39], 10, v[38:39]
	v_lshl_add_u64 v[38:39], v[40:41], 0, v[38:39]
	global_load_dwordx2 v[38:39], v[38:39], off

; template <bool FULL>
; DI void ssm_item(const P& p, int l, int item, char* smem) {
;     ...
; #pragma unroll 4
;     for (int t = 0; t < 16; ++t) {
;       const float4* up = (const float4*)(us + t * 16);
;       const float4 u0 = up[0], u1 = up[1], u2 = up[2], u3 = up[3];
;       const float uu[16] = {u0.x, u0.y, u0.z, u0.w, u1.x, u1.y, u1.z, u1.w, u2.x, u2.y, u2.z, u2.w, u3.x, u3.y, u3.z, u3.w};
;       float br = 0.f, bi = 0.f;
; #pragma unroll
;       for (int i = 0; i < 16; ++i) { br = fmaf(bbr[i], uu[i], br); bi = fmaf(bbi[i], uu[i], bi); }
;       const float nhr = ar * hr - ai * hi + br, nhi = ar * hi + ai * hr + bi;
;       hr = nhr; hi = nhi;
;       if (FULL) { H[t * 132 + lane] = hr; H[t * 132 + 64 + lane] = hi; }
;     }
.LBB0_173:
	v_add_u32_e32 v154, v86, v46
	ds_read_b128 v[112:115], v46 offset:8448
	ds_read_b128 v[116:119], v46 offset:8464
	ds_read_b128 v[120:123], v46 offset:8480
	ds_read_b128 v[124:127], v46 offset:8496
	ds_read_b128 v[128:131], v46 offset:8512
	ds_read_b128 v[132:135], v46 offset:8528
	ds_read_b128 v[136:139], v46 offset:8544
	ds_read_b128 v[140:143], v46 offset:8560
	s_waitcnt lgkmcnt(4)
	v_mul_f32_e32 v144, v12, v112
	v_mul_f32_e32 v145, v13, v112
	v_mul_f32_e32 v146, v4, v116
	v_mul_f32_e32 v147, v5, v116
	v_mul_f32_e32 v148, v32, v120
	v_mul_f32_e32 v149, v33, v120
	v_mul_f32_e32 v150, v24, v124
	v_mul_f32_e32 v151, v25, v124
	v_fmac_f32_e32 v144, v14, v113
	v_fmac_f32_e32 v145, v15, v113
	v_fmac_f32_e32 v146, v6, v117
	v_fmac_f32_e32 v147, v7, v117
	v_fmac_f32_e32 v148, v34, v121
	v_fmac_f32_e32 v149, v35, v121
	v_fmac_f32_e32 v150, v26, v125
	v_fmac_f32_e32 v151, v27, v125
	v_fmac_f32_e32 v144, v8, v114
	v_fmac_f32_e32 v145, v9, v114
	v_fmac_f32_e32 v146, v0, v118
	v_fmac_f32_e32 v147, v1, v118
	v_fmac_f32_e32 v148, v28, v122
	v_fmac_f32_e32 v149, v29, v122
	v_fmac_f32_e32 v150, v20, v126
	v_fmac_f32_e32 v151, v21, v126
	v_fmac_f32_e32 v144, v10, v115
	v_fmac_f32_e32 v145, v11, v115
	v_fmac_f32_e32 v146, v2, v119
	v_fmac_f32_e32 v147, v3, v119
	v_fmac_f32_e32 v148, v30, v123
	v_fmac_f32_e32 v149, v31, v123
	v_fmac_f32_e32 v150, v22, v127
	v_fmac_f32_e32 v151, v23, v127
	v_add_f32_e32 v144, v144, v146
	v_add_f32_e32 v145, v145, v147
	v_add_f32_e32 v148, v148, v150
	v_add_f32_e32 v149, v149, v151
	v_add_f32_e32 v144, v144, v148
	v_add_f32_e32 v145, v145, v149
	v_fma_f32 v152, -v17, v37, v144
	v_fma_f32 v153, v17, v36, v145
	v_fma_f32 v36, v16, v36, v152
	v_fma_f32 v37, v16, v37, v153
	ds_write_b32 v154, v36 offset:0
	ds_write_b32 v154, v37 offset:256
	ds_read_b128 v[112:115], v46 offset:8576
	ds_read_b128 v[116:119], v46 offset:8592
	ds_read_b128 v[120:123], v46 offset:8608
	ds_read_b128 v[124:127], v46 offset:8624
	s_waitcnt lgkmcnt(6)
	v_mul_f32_e32 v144, v12, v128
	v_mul_f32_e32 v145, v13, v128
	v_mul_f32_e32 v146, v4, v132
	v_mul_f32_e32 v147, v5, v132
	v_mul_f32_e32 v148, v32, v136
	v_mul_f32_e32 v149, v33, v136
	v_mul_f32_e32 v150, v24, v140
	v_mul_f32_e32 v151, v25, v140
	v_fmac_f32_e32 v144, v14, v129
	v_fmac_f32_e32 v145, v15, v129
	v_fmac_f32_e32 v146, v6, v133
	v_fmac_f32_e32 v147, v7, v133
	v_fmac_f32_e32 v148, v34, v137
	v_fmac_f32_e32 v149, v35, v137
	v_fmac_f32_e32 v150, v26, v141
	v_fmac_f32_e32 v151, v27, v141
	v_fmac_f32_e32 v144, v8, v130
	v_fmac_f32_e32 v145, v9, v130
	v_fmac_f32_e32 v146, v0, v134
	v_fmac_f32_e32 v147, v1, v134
	v_fmac_f32_e32 v148, v28, v138
	v_fmac_f32_e32 v149, v29, v138
	v_fmac_f32_e32 v150, v20, v142
	v_fmac_f32_e32 v151, v21, v142
	v_fmac_f32_e32 v144, v10, v131
	v_fmac_f32_e32 v145, v11, v131
	v_fmac_f32_e32 v146, v2, v135
	v_fmac_f32_e32 v147, v3, v135
	v_fmac_f32_e32 v148, v30, v139
	v_fmac_f32_e32 v149, v31, v139
	v_fmac_f32_e32 v150, v22, v143
	v_fmac_f32_e32 v151, v23, v143
	v_add_f32_e32 v144, v144, v146
	v_add_f32_e32 v145, v145, v147
	v_add_f32_e32 v148, v148, v150
	v_add_f32_e32 v149, v149, v151
	v_add_f32_e32 v144, v144, v148
	v_add_f32_e32 v145, v145, v149
	v_fma_f32 v152, -v17, v37, v144
	v_fma_f32 v153, v17, v36, v145
	v_fma_f32 v36, v16, v36, v152
	v_fma_f32 v37, v16, v37, v153
	ds_write_b32 v154, v36 offset:528
	ds_write_b32 v154, v37 offset:784
	ds_read_b128 v[128:131], v46 offset:8640
	ds_read_b128 v[132:135], v46 offset:8656
	ds_read_b128 v[136:139], v46 offset:8672
	ds_read_b128 v[140:143], v46 offset:8688
	s_waitcnt lgkmcnt(6)
	v_mul_f32_e32 v144, v12, v112
	v_mul_f32_e32 v145, v13, v112
	v_mul_f32_e32 v146, v4, v116
	v_mul_f32_e32 v147, v5, v116
	v_mul_f32_e32 v148, v32, v120
	v_mul_f32_e32 v149, v33, v120
	v_mul_f32_e32 v150, v24, v124
	v_mul_f32_e32 v151, v25, v124
	v_fmac_f32_e32 v144, v14, v113
	v_fmac_f32_e32 v145, v15, v113
	v_fmac_f32_e32 v146, v6, v117
	v_fmac_f32_e32 v147, v7, v117
	v_fmac_f32_e32 v148, v34, v121
	v_fmac_f32_e32 v149, v35, v121
	v_fmac_f32_e32 v150, v26, v125
	v_fmac_f32_e32 v151, v27, v125
	v_fmac_f32_e32 v144, v8, v114
	v_fmac_f32_e32 v145, v9, v114
	v_fmac_f32_e32 v146, v0, v118
	v_fmac_f32_e32 v147, v1, v118
	v_fmac_f32_e32 v148, v28, v122
	v_fmac_f32_e32 v149, v29, v122
	v_fmac_f32_e32 v150, v20, v126
	v_fmac_f32_e32 v151, v21, v126
	v_fmac_f32_e32 v144, v10, v115
	v_fmac_f32_e32 v145, v11, v115
	v_fmac_f32_e32 v146, v2, v119
	v_fmac_f32_e32 v147, v3, v119
	v_fmac_f32_e32 v148, v30, v123
	v_fmac_f32_e32 v149, v31, v123
	v_fmac_f32_e32 v150, v22, v127
	v_fmac_f32_e32 v151, v23, v127
	v_add_f32_e32 v144, v144, v146
	v_add_f32_e32 v145, v145, v147
	v_add_f32_e32 v148, v148, v150
	v_add_f32_e32 v149, v149, v151
	v_add_f32_e32 v144, v144, v148
	v_add_f32_e32 v145, v145, v149
	v_fma_f32 v152, -v17, v37, v144
	v_fma_f32 v153, v17, v36, v145
	v_fma_f32 v36, v16, v36, v152
	v_fma_f32 v37, v16, v37, v153
	ds_write_b32 v154, v36 offset:1056
	ds_write_b32 v154, v37 offset:1312
	ds_read_b128 v[112:115], v46 offset:8704
	ds_read_b128 v[116:119], v46 offset:8720
	ds_read_b128 v[120:123], v46 offset:8736
	ds_read_b128 v[124:127], v46 offset:8752
	s_waitcnt lgkmcnt(6)
; template <bool FULL>
; DI void ssm_item(const P& p, int l, int item, char* smem) {
;     ...
;     for (int t = 0; t < 16; ++t) {
;       const float4* up = (const float4*)(us + t * 16);
;       const float4 u0 = up[0], u1 = up[1], u2 = up[2], u3 = up[3];
;       const float uu[16] = {u0.x, u0.y, u0.z, u0.w, u1.x, u1.y, u1.z, u1.w, u2.x, u2.y, u2.z, u2.w, u3.x, u3.y, u3.z, u3.w};
;       float br = 0.f, bi = 0.f;
; #pragma unroll
;       for (int i = 0; i < 16; ++i) { br = fmaf(bbr[i], uu[i], br); bi = fmaf(bbi[i], uu[i], bi); }
;       const float nhr = ar * hr - ai * hi + br, nhi = ar * hi + ai * hr + bi;
;       hr = nhr; hi = nhi;
;       if (FULL) { H[t * 132 + lane] = hr; H[t * 132 + 64 + lane] = hi; }
	v_mul_f32_e32 v144, v12, v128
	v_mul_f32_e32 v145, v13, v128
	v_mul_f32_e32 v146, v4, v132
	v_mul_f32_e32 v147, v5, v132
	v_mul_f32_e32 v148, v32, v136
	v_mul_f32_e32 v149, v33, v136
	v_mul_f32_e32 v150, v24, v140
	v_mul_f32_e32 v151, v25, v140
	v_fmac_f32_e32 v144, v14, v129
	v_fmac_f32_e32 v145, v15, v129
	v_fmac_f32_e32 v146, v6, v133
	v_fmac_f32_e32 v147, v7, v133
	v_fmac_f32_e32 v148, v34, v137
	v_fmac_f32_e32 v149, v35, v137
	v_fmac_f32_e32 v150, v26, v141
	v_fmac_f32_e32 v151, v27, v141
	v_fmac_f32_e32 v144, v8, v130
	v_fmac_f32_e32 v145, v9, v130
	v_fmac_f32_e32 v146, v0, v134
	v_fmac_f32_e32 v147, v1, v134
	v_fmac_f32_e32 v148, v28, v138
	v_fmac_f32_e32 v149, v29, v138
	v_fmac_f32_e32 v150, v20, v142
	v_fmac_f32_e32 v151, v21, v142
	v_fmac_f32_e32 v144, v10, v131
	v_fmac_f32_e32 v145, v11, v131
	v_fmac_f32_e32 v146, v2, v135
	v_fmac_f32_e32 v147, v3, v135
	v_fmac_f32_e32 v148, v30, v139
	v_fmac_f32_e32 v149, v31, v139
	v_fmac_f32_e32 v150, v22, v143
	v_fmac_f32_e32 v151, v23, v143
	v_add_f32_e32 v144, v144, v146
	v_add_f32_e32 v145, v145, v147
	v_add_f32_e32 v148, v148, v150
	v_add_f32_e32 v149, v149, v151
	v_add_f32_e32 v144, v144, v148
	v_add_f32_e32 v145, v145, v149
	v_fma_f32 v152, -v17, v37, v144
	v_fma_f32 v153, v17, v36, v145
	v_fma_f32 v36, v16, v36, v152
	v_fma_f32 v37, v16, v37, v153
	ds_write_b32 v154, v36 offset:1584
	ds_write_b32 v154, v37 offset:1840
	ds_read_b128 v[128:131], v46 offset:8768
	ds_read_b128 v[132:135], v46 offset:8784
	ds_read_b128 v[136:139], v46 offset:8800
	ds_read_b128 v[140:143], v46 offset:8816
	s_waitcnt lgkmcnt(6)
	v_mul_f32_e32 v144, v12, v112
	v_mul_f32_e32 v145, v13, v112
	v_mul_f32_e32 v146, v4, v116
	v_mul_f32_e32 v147, v5, v116
	v_mul_f32_e32 v148, v32, v120
	v_mul_f32_e32 v149, v33, v120
	v_mul_f32_e32 v150, v24, v124
	v_mul_f32_e32 v151, v25, v124
	v_fmac_f32_e32 v144, v14, v113
	v_fmac_f32_e32 v145, v15, v113
	v_fmac_f32_e32 v146, v6, v117
	v_fmac_f32_e32 v147, v7, v117
	v_fmac_f32_e32 v148, v34, v121
	v_fmac_f32_e32 v149, v35, v121
	v_fmac_f32_e32 v150, v26, v125
	v_fmac_f32_e32 v151, v27, v125
	v_fmac_f32_e32 v144, v8, v114
	v_fmac_f32_e32 v145, v9, v114
	v_fmac_f32_e32 v146, v0, v118
	v_fmac_f32_e32 v147, v1, v118
	v_fmac_f32_e32 v148, v28, v122
	v_fmac_f32_e32 v149, v29, v122
	v_fmac_f32_e32 v150, v20, v126
	v_fmac_f32_e32 v151, v21, v126
	v_fmac_f32_e32 v144, v10, v115
	v_fmac_f32_e32 v145, v11, v115
	v_fmac_f32_e32 v146, v2, v119
	v_fmac_f32_e32 v147, v3, v119
	v_fmac_f32_e32 v148, v30, v123
	v_fmac_f32_e32 v149, v31, v123
	v_fmac_f32_e32 v150, v22, v127
	v_fmac_f32_e32 v151, v23, v127
	v_add_f32_e32 v144, v144, v146
	v_add_f32_e32 v145, v145, v147
	v_add_f32_e32 v148, v148, v150
	v_add_f32_e32 v149, v149, v151
	v_add_f32_e32 v144, v144, v148
	v_add_f32_e32 v145, v145, v149
	v_fma_f32 v152, -v17, v37, v144
	v_fma_f32 v153, v17, v36, v145
	v_fma_f32 v36, v16, v36, v152
	v_fma_f32 v37, v16, v37, v153
	ds_write_b32 v154, v36 offset:2112
	ds_write_b32 v154, v37 offset:2368
	ds_read_b128 v[112:115], v46 offset:8832
	ds_read_b128 v[116:119], v46 offset:8848
	ds_read_b128 v[120:123], v46 offset:8864
	ds_read_b128 v[124:127], v46 offset:8880
	s_waitcnt lgkmcnt(6)
	v_mul_f32_e32 v144, v12, v128
	v_mul_f32_e32 v145, v13, v128
	v_mul_f32_e32 v146, v4, v132
	v_mul_f32_e32 v147, v5, v132
	v_mul_f32_e32 v148, v32, v136
	v_mul_f32_e32 v149, v33, v136
	v_mul_f32_e32 v150, v24, v140
	v_mul_f32_e32 v151, v25, v140
	v_fmac_f32_e32 v144, v14, v129
	v_fmac_f32_e32 v145, v15, v129
	v_fmac_f32_e32 v146, v6, v133
	v_fmac_f32_e32 v147, v7, v133
	v_fmac_f32_e32 v148, v34, v137
	v_fmac_f32_e32 v149, v35, v137
	v_fmac_f32_e32 v150, v26, v141
	v_fmac_f32_e32 v151, v27, v141
	v_fmac_f32_e32 v144, v8, v130
	v_fmac_f32_e32 v145, v9, v130
	v_fmac_f32_e32 v146, v0, v134
	v_fmac_f32_e32 v147, v1, v134
	v_fmac_f32_e32 v148, v28, v138
	v_fmac_f32_e32 v149, v29, v138
	v_fmac_f32_e32 v150, v20, v142
	v_fmac_f32_e32 v151, v21, v142
	v_fmac_f32_e32 v144, v10, v131
	v_fmac_f32_e32 v145, v11, v131
	v_fmac_f32_e32 v146, v2, v135
	v_fmac_f32_e32 v147, v3, v135
	v_fmac_f32_e32 v148, v30, v139
	v_fmac_f32_e32 v149, v31, v139
	v_fmac_f32_e32 v150, v22, v143
	v_fmac_f32_e32 v151, v23, v143
	v_add_f32_e32 v144, v144, v146
	v_add_f32_e32 v145, v145, v147
	v_add_f32_e32 v148, v148, v150
	v_add_f32_e32 v149, v149, v151
	v_add_f32_e32 v144, v144, v148
	v_add_f32_e32 v145, v145, v149
	v_fma_f32 v152, -v17, v37, v144
	v_fma_f32 v153, v17, v36, v145
	v_fma_f32 v36, v16, v36, v152
	v_fma_f32 v37, v16, v37, v153
	ds_write_b32 v154, v36 offset:2640
	ds_write_b32 v154, v37 offset:2896
	ds_read_b128 v[128:131], v46 offset:8896
	ds_read_b128 v[132:135], v46 offset:8912
	ds_read_b128 v[136:139], v46 offset:8928
	ds_read_b128 v[140:143], v46 offset:8944
	s_waitcnt lgkmcnt(6)
	v_mul_f32_e32 v144, v12, v112
	v_mul_f32_e32 v145, v13, v112
	v_mul_f32_e32 v146, v4, v116
	v_mul_f32_e32 v147, v5, v116
	v_mul_f32_e32 v148, v32, v120
	v_mul_f32_e32 v149, v33, v120
	v_mul_f32_e32 v150, v24, v124
	v_mul_f32_e32 v151, v25, v124
	v_fmac_f32_e32 v144, v14, v113
	v_fmac_f32_e32 v145, v15, v113
	v_fmac_f32_e32 v146, v6, v117
	v_fmac_f32_e32 v147, v7, v117
	v_fmac_f32_e32 v148, v34, v121
	v_fmac_f32_e32 v149, v35, v121
	v_fmac_f32_e32 v150, v26, v125
	v_fmac_f32_e32 v151, v27, v125
	v_fmac_f32_e32 v144, v8, v114
	v_fmac_f32_e32 v145, v9, v114
	v_fmac_f32_e32 v146, v0, v118
	v_fmac_f32_e32 v147, v1, v118
	v_fmac_f32_e32 v148, v28, v122
	v_fmac_f32_e32 v149, v29, v122
	v_fmac_f32_e32 v150, v20, v126
	v_fmac_f32_e32 v151, v21, v126
	v_fmac_f32_e32 v144, v10, v115
	v_fmac_f32_e32 v145, v11, v115
	v_fmac_f32_e32 v146, v2, v119
	v_fmac_f32_e32 v147, v3, v119
	v_fmac_f32_e32 v148, v30, v123
	v_fmac_f32_e32 v149, v31, v123
	v_fmac_f32_e32 v150, v22, v127
	v_fmac_f32_e32 v151, v23, v127
	v_add_f32_e32 v144, v144, v146
	v_add_f32_e32 v145, v145, v147
	v_add_f32_e32 v148, v148, v150
	v_add_f32_e32 v149, v149, v151
	v_add_f32_e32 v144, v144, v148
	v_add_f32_e32 v145, v145, v149
	v_fma_f32 v152, -v17, v37, v144
	v_fma_f32 v153, v17, v36, v145
	v_fma_f32 v36, v16, v36, v152
	v_fma_f32 v37, v16, v37, v153
	ds_write_b32 v154, v36 offset:3168
	ds_write_b32 v154, v37 offset:3424
	ds_read_b128 v[112:115], v46 offset:8960
	ds_read_b128 v[116:119], v46 offset:8976
	ds_read_b128 v[120:123], v46 offset:8992
	ds_read_b128 v[124:127], v46 offset:9008
	s_waitcnt lgkmcnt(6)
; template <bool FULL>
; DI void ssm_item(const P& p, int l, int item, char* smem) {
;     ...
;     for (int t = 0; t < 16; ++t) {
;       const float4* up = (const float4*)(us + t * 16);
;       const float4 u0 = up[0], u1 = up[1], u2 = up[2], u3 = up[3];
;       const float uu[16] = {u0.x, u0.y, u0.z, u0.w, u1.x, u1.y, u1.z, u1.w, u2.x, u2.y, u2.z, u2.w, u3.x, u3.y, u3.z, u3.w};
;       float br = 0.f, bi = 0.f;
; #pragma unroll
;       for (int i = 0; i < 16; ++i) { br = fmaf(bbr[i], uu[i], br); bi = fmaf(bbi[i], uu[i], bi); }
;       const float nhr = ar * hr - ai * hi + br, nhi = ar * hi + ai * hr + bi;
;       hr = nhr; hi = nhi;
;       if (FULL) { H[t * 132 + lane] = hr; H[t * 132 + 64 + lane] = hi; }
	v_mul_f32_e32 v144, v12, v128
	v_mul_f32_e32 v145, v13, v128
	v_mul_f32_e32 v146, v4, v132
	v_mul_f32_e32 v147, v5, v132
	v_mul_f32_e32 v148, v32, v136
	v_mul_f32_e32 v149, v33, v136
	v_mul_f32_e32 v150, v24, v140
	v_mul_f32_e32 v151, v25, v140
	v_fmac_f32_e32 v144, v14, v129
	v_fmac_f32_e32 v145, v15, v129
	v_fmac_f32_e32 v146, v6, v133
	v_fmac_f32_e32 v147, v7, v133
	v_fmac_f32_e32 v148, v34, v137
	v_fmac_f32_e32 v149, v35, v137
	v_fmac_f32_e32 v150, v26, v141
	v_fmac_f32_e32 v151, v27, v141
	v_fmac_f32_e32 v144, v8, v130
	v_fmac_f32_e32 v145, v9, v130
	v_fmac_f32_e32 v146, v0, v134
	v_fmac_f32_e32 v147, v1, v134
	v_fmac_f32_e32 v148, v28, v138
	v_fmac_f32_e32 v149, v29, v138
	v_fmac_f32_e32 v150, v20, v142
	v_fmac_f32_e32 v151, v21, v142
	v_fmac_f32_e32 v144, v10, v131
	v_fmac_f32_e32 v145, v11, v131
	v_fmac_f32_e32 v146, v2, v135
	v_fmac_f32_e32 v147, v3, v135
	v_fmac_f32_e32 v148, v30, v139
	v_fmac_f32_e32 v149, v31, v139
	v_fmac_f32_e32 v150, v22, v143
	v_fmac_f32_e32 v151, v23, v143
	v_add_f32_e32 v144, v144, v146
	v_add_f32_e32 v145, v145, v147
	v_add_f32_e32 v148, v148, v150
	v_add_f32_e32 v149, v149, v151
	v_add_f32_e32 v144, v144, v148
	v_add_f32_e32 v145, v145, v149
	v_fma_f32 v152, -v17, v37, v144
	v_fma_f32 v153, v17, v36, v145
	v_fma_f32 v36, v16, v36, v152
	v_fma_f32 v37, v16, v37, v153
	ds_write_b32 v154, v36 offset:3696
	ds_write_b32 v154, v37 offset:3952
	ds_read_b128 v[128:131], v46 offset:9024
	ds_read_b128 v[132:135], v46 offset:9040
	ds_read_b128 v[136:139], v46 offset:9056
	ds_read_b128 v[140:143], v46 offset:9072
	s_waitcnt lgkmcnt(6)
	v_mul_f32_e32 v144, v12, v112
	v_mul_f32_e32 v145, v13, v112
	v_mul_f32_e32 v146, v4, v116
	v_mul_f32_e32 v147, v5, v116
	v_mul_f32_e32 v148, v32, v120
	v_mul_f32_e32 v149, v33, v120
	v_mul_f32_e32 v150, v24, v124
	v_mul_f32_e32 v151, v25, v124
	v_fmac_f32_e32 v144, v14, v113
	v_fmac_f32_e32 v145, v15, v113
	v_fmac_f32_e32 v146, v6, v117
	v_fmac_f32_e32 v147, v7, v117
	v_fmac_f32_e32 v148, v34, v121
	v_fmac_f32_e32 v149, v35, v121
	v_fmac_f32_e32 v150, v26, v125
	v_fmac_f32_e32 v151, v27, v125
	v_fmac_f32_e32 v144, v8, v114
	v_fmac_f32_e32 v145, v9, v114
	v_fmac_f32_e32 v146, v0, v118
	v_fmac_f32_e32 v147, v1, v118
	v_fmac_f32_e32 v148, v28, v122
	v_fmac_f32_e32 v149, v29, v122
	v_fmac_f32_e32 v150, v20, v126
	v_fmac_f32_e32 v151, v21, v126
	v_fmac_f32_e32 v144, v10, v115
	v_fmac_f32_e32 v145, v11, v115
	v_fmac_f32_e32 v146, v2, v119
	v_fmac_f32_e32 v147, v3, v119
	v_fmac_f32_e32 v148, v30, v123
	v_fmac_f32_e32 v149, v31, v123
	v_fmac_f32_e32 v150, v22, v127
	v_fmac_f32_e32 v151, v23, v127
	v_add_f32_e32 v144, v144, v146
	v_add_f32_e32 v145, v145, v147
	v_add_f32_e32 v148, v148, v150
	v_add_f32_e32 v149, v149, v151
	v_add_f32_e32 v144, v144, v148
	v_add_f32_e32 v145, v145, v149
	v_fma_f32 v152, -v17, v37, v144
	v_fma_f32 v153, v17, v36, v145
	v_fma_f32 v36, v16, v36, v152
	v_fma_f32 v37, v16, v37, v153
	ds_write_b32 v154, v36 offset:4224
	ds_write_b32 v154, v37 offset:4480
	ds_read_b128 v[112:115], v46 offset:9088
	ds_read_b128 v[116:119], v46 offset:9104
	ds_read_b128 v[120:123], v46 offset:9120
	ds_read_b128 v[124:127], v46 offset:9136
	s_waitcnt lgkmcnt(6)
	v_mul_f32_e32 v144, v12, v128
	v_mul_f32_e32 v145, v13, v128
	v_mul_f32_e32 v146, v4, v132
	v_mul_f32_e32 v147, v5, v132
	v_mul_f32_e32 v148, v32, v136
	v_mul_f32_e32 v149, v33, v136
	v_mul_f32_e32 v150, v24, v140
	v_mul_f32_e32 v151, v25, v140
	v_fmac_f32_e32 v144, v14, v129
	v_fmac_f32_e32 v145, v15, v129
	v_fmac_f32_e32 v146, v6, v133
	v_fmac_f32_e32 v147, v7, v133
	v_fmac_f32_e32 v148, v34, v137
	v_fmac_f32_e32 v149, v35, v137
	v_fmac_f32_e32 v150, v26, v141
	v_fmac_f32_e32 v151, v27, v141
	v_fmac_f32_e32 v144, v8, v130
	v_fmac_f32_e32 v145, v9, v130
	v_fmac_f32_e32 v146, v0, v134
	v_fmac_f32_e32 v147, v1, v134
	v_fmac_f32_e32 v148, v28, v138
	v_fmac_f32_e32 v149, v29, v138
	v_fmac_f32_e32 v150, v20, v142
	v_fmac_f32_e32 v151, v21, v142
	v_fmac_f32_e32 v144, v10, v131
	v_fmac_f32_e32 v145, v11, v131
	v_fmac_f32_e32 v146, v2, v135
	v_fmac_f32_e32 v147, v3, v135
	v_fmac_f32_e32 v148, v30, v139
	v_fmac_f32_e32 v149, v31, v139
	v_fmac_f32_e32 v150, v22, v143
	v_fmac_f32_e32 v151, v23, v143
	v_add_f32_e32 v144, v144, v146
	v_add_f32_e32 v145, v145, v147
	v_add_f32_e32 v148, v148, v150
	v_add_f32_e32 v149, v149, v151
	v_add_f32_e32 v144, v144, v148
	v_add_f32_e32 v145, v145, v149
	v_fma_f32 v152, -v17, v37, v144
	v_fma_f32 v153, v17, v36, v145
	v_fma_f32 v36, v16, v36, v152
	v_fma_f32 v37, v16, v37, v153
	ds_write_b32 v154, v36 offset:4752
	ds_write_b32 v154, v37 offset:5008
	ds_read_b128 v[128:131], v46 offset:9152
	ds_read_b128 v[132:135], v46 offset:9168
	ds_read_b128 v[136:139], v46 offset:9184
	ds_read_b128 v[140:143], v46 offset:9200
	s_waitcnt lgkmcnt(6)
	v_mul_f32_e32 v144, v12, v112
	v_mul_f32_e32 v145, v13, v112
	v_mul_f32_e32 v146, v4, v116
	v_mul_f32_e32 v147, v5, v116
	v_mul_f32_e32 v148, v32, v120
	v_mul_f32_e32 v149, v33, v120
	v_mul_f32_e32 v150, v24, v124
	v_mul_f32_e32 v151, v25, v124
	v_fmac_f32_e32 v144, v14, v113
	v_fmac_f32_e32 v145, v15, v113
	v_fmac_f32_e32 v146, v6, v117
	v_fmac_f32_e32 v147, v7, v117
	v_fmac_f32_e32 v148, v34, v121
	v_fmac_f32_e32 v149, v35, v121
	v_fmac_f32_e32 v150, v26, v125
	v_fmac_f32_e32 v151, v27, v125
	v_fmac_f32_e32 v144, v8, v114
	v_fmac_f32_e32 v145, v9, v114
	v_fmac_f32_e32 v146, v0, v118
	v_fmac_f32_e32 v147, v1, v118
	v_fmac_f32_e32 v148, v28, v122
	v_fmac_f32_e32 v149, v29, v122
	v_fmac_f32_e32 v150, v20, v126
	v_fmac_f32_e32 v151, v21, v126
	v_fmac_f32_e32 v144, v10, v115
	v_fmac_f32_e32 v145, v11, v115
	v_fmac_f32_e32 v146, v2, v119
	v_fmac_f32_e32 v147, v3, v119
	v_fmac_f32_e32 v148, v30, v123
	v_fmac_f32_e32 v149, v31, v123
	v_fmac_f32_e32 v150, v22, v127
	v_fmac_f32_e32 v151, v23, v127
	v_add_f32_e32 v144, v144, v146
	v_add_f32_e32 v145, v145, v147
	v_add_f32_e32 v148, v148, v150
	v_add_f32_e32 v149, v149, v151
	v_add_f32_e32 v144, v144, v148
	v_add_f32_e32 v145, v145, v149
	v_fma_f32 v152, -v17, v37, v144
	v_fma_f32 v153, v17, v36, v145
	v_fma_f32 v36, v16, v36, v152
	v_fma_f32 v37, v16, v37, v153
	ds_write_b32 v154, v36 offset:5280
	ds_write_b32 v154, v37 offset:5536
	ds_read_b128 v[112:115], v46 offset:9216
	ds_read_b128 v[116:119], v46 offset:9232
	ds_read_b128 v[120:123], v46 offset:9248
	ds_read_b128 v[124:127], v46 offset:9264
	s_waitcnt lgkmcnt(6)
; template <bool FULL>
; DI void ssm_item(const P& p, int l, int item, char* smem) {
;     ...
;     for (int t = 0; t < 16; ++t) {
;       const float4* up = (const float4*)(us + t * 16);
;       const float4 u0 = up[0], u1 = up[1], u2 = up[2], u3 = up[3];
;       const float uu[16] = {u0.x, u0.y, u0.z, u0.w, u1.x, u1.y, u1.z, u1.w, u2.x, u2.y, u2.z, u2.w, u3.x, u3.y, u3.z, u3.w};
;       float br = 0.f, bi = 0.f;
; #pragma unroll
;       for (int i = 0; i < 16; ++i) { br = fmaf(bbr[i], uu[i], br); bi = fmaf(bbi[i], uu[i], bi); }
;       const float nhr = ar * hr - ai * hi + br, nhi = ar * hi + ai * hr + bi;
;       hr = nhr; hi = nhi;
;       if (FULL) { H[t * 132 + lane] = hr; H[t * 132 + 64 + lane] = hi; }
	v_mul_f32_e32 v144, v12, v128
	v_mul_f32_e32 v145, v13, v128
	v_mul_f32_e32 v146, v4, v132
	v_mul_f32_e32 v147, v5, v132
	v_mul_f32_e32 v148, v32, v136
	v_mul_f32_e32 v149, v33, v136
	v_mul_f32_e32 v150, v24, v140
	v_mul_f32_e32 v151, v25, v140
	v_fmac_f32_e32 v144, v14, v129
	v_fmac_f32_e32 v145, v15, v129
	v_fmac_f32_e32 v146, v6, v133
	v_fmac_f32_e32 v147, v7, v133
	v_fmac_f32_e32 v148, v34, v137
	v_fmac_f32_e32 v149, v35, v137
	v_fmac_f32_e32 v150, v26, v141
	v_fmac_f32_e32 v151, v27, v141
	v_fmac_f32_e32 v144, v8, v130
	v_fmac_f32_e32 v145, v9, v130
	v_fmac_f32_e32 v146, v0, v134
	v_fmac_f32_e32 v147, v1, v134
	v_fmac_f32_e32 v148, v28, v138
	v_fmac_f32_e32 v149, v29, v138
	v_fmac_f32_e32 v150, v20, v142
	v_fmac_f32_e32 v151, v21, v142
	v_fmac_f32_e32 v144, v10, v131
	v_fmac_f32_e32 v145, v11, v131
	v_fmac_f32_e32 v146, v2, v135
	v_fmac_f32_e32 v147, v3, v135
	v_fmac_f32_e32 v148, v30, v139
	v_fmac_f32_e32 v149, v31, v139
	v_fmac_f32_e32 v150, v22, v143
	v_fmac_f32_e32 v151, v23, v143
	v_add_f32_e32 v144, v144, v146
	v_add_f32_e32 v145, v145, v147
	v_add_f32_e32 v148, v148, v150
	v_add_f32_e32 v149, v149, v151
	v_add_f32_e32 v144, v144, v148
	v_add_f32_e32 v145, v145, v149
	v_fma_f32 v152, -v17, v37, v144
	v_fma_f32 v153, v17, v36, v145
	v_fma_f32 v36, v16, v36, v152
	v_fma_f32 v37, v16, v37, v153
	ds_write_b32 v154, v36 offset:5808
	ds_write_b32 v154, v37 offset:6064
	ds_read_b128 v[128:131], v46 offset:9280
	ds_read_b128 v[132:135], v46 offset:9296
	ds_read_b128 v[136:139], v46 offset:9312
	ds_read_b128 v[140:143], v46 offset:9328
	s_waitcnt lgkmcnt(6)
	v_mul_f32_e32 v144, v12, v112
	v_mul_f32_e32 v145, v13, v112
	v_mul_f32_e32 v146, v4, v116
	v_mul_f32_e32 v147, v5, v116
	v_mul_f32_e32 v148, v32, v120
	v_mul_f32_e32 v149, v33, v120
	v_mul_f32_e32 v150, v24, v124
	v_mul_f32_e32 v151, v25, v124
	v_fmac_f32_e32 v144, v14, v113
	v_fmac_f32_e32 v145, v15, v113
	v_fmac_f32_e32 v146, v6, v117
	v_fmac_f32_e32 v147, v7, v117
	v_fmac_f32_e32 v148, v34, v121
	v_fmac_f32_e32 v149, v35, v121
	v_fmac_f32_e32 v150, v26, v125
	v_fmac_f32_e32 v151, v27, v125
	v_fmac_f32_e32 v144, v8, v114
	v_fmac_f32_e32 v145, v9, v114
	v_fmac_f32_e32 v146, v0, v118
	v_fmac_f32_e32 v147, v1, v118
	v_fmac_f32_e32 v148, v28, v122
	v_fmac_f32_e32 v149, v29, v122
	v_fmac_f32_e32 v150, v20, v126
	v_fmac_f32_e32 v151, v21, v126
	v_fmac_f32_e32 v144, v10, v115
	v_fmac_f32_e32 v145, v11, v115
	v_fmac_f32_e32 v146, v2, v119
	v_fmac_f32_e32 v147, v3, v119
	v_fmac_f32_e32 v148, v30, v123
	v_fmac_f32_e32 v149, v31, v123
	v_fmac_f32_e32 v150, v22, v127
	v_fmac_f32_e32 v151, v23, v127
	v_add_f32_e32 v144, v144, v146
	v_add_f32_e32 v145, v145, v147
	v_add_f32_e32 v148, v148, v150
	v_add_f32_e32 v149, v149, v151
	v_add_f32_e32 v144, v144, v148
	v_add_f32_e32 v145, v145, v149
	v_fma_f32 v152, -v17, v37, v144
	v_fma_f32 v153, v17, v36, v145
	v_fma_f32 v36, v16, v36, v152
	v_fma_f32 v37, v16, v37, v153
	ds_write_b32 v154, v36 offset:6336
	ds_write_b32 v154, v37 offset:6592
	ds_read_b128 v[112:115], v46 offset:9344
	ds_read_b128 v[116:119], v46 offset:9360
	ds_read_b128 v[120:123], v46 offset:9376
	ds_read_b128 v[124:127], v46 offset:9392
	s_waitcnt lgkmcnt(6)
	v_mul_f32_e32 v144, v12, v128
	v_mul_f32_e32 v145, v13, v128
	v_mul_f32_e32 v146, v4, v132
	v_mul_f32_e32 v147, v5, v132
	v_mul_f32_e32 v148, v32, v136
	v_mul_f32_e32 v149, v33, v136
	v_mul_f32_e32 v150, v24, v140
	v_mul_f32_e32 v151, v25, v140
	v_fmac_f32_e32 v144, v14, v129
	v_fmac_f32_e32 v145, v15, v129
	v_fmac_f32_e32 v146, v6, v133
	v_fmac_f32_e32 v147, v7, v133
	v_fmac_f32_e32 v148, v34, v137
	v_fmac_f32_e32 v149, v35, v137
	v_fmac_f32_e32 v150, v26, v141
	v_fmac_f32_e32 v151, v27, v141
	v_fmac_f32_e32 v144, v8, v130
	v_fmac_f32_e32 v145, v9, v130
	v_fmac_f32_e32 v146, v0, v134
	v_fmac_f32_e32 v147, v1, v134
	v_fmac_f32_e32 v148, v28, v138
	v_fmac_f32_e32 v149, v29, v138
	v_fmac_f32_e32 v150, v20, v142
	v_fmac_f32_e32 v151, v21, v142
	v_fmac_f32_e32 v144, v10, v131
	v_fmac_f32_e32 v145, v11, v131
	v_fmac_f32_e32 v146, v2, v135
	v_fmac_f32_e32 v147, v3, v135
	v_fmac_f32_e32 v148, v30, v139
	v_fmac_f32_e32 v149, v31, v139
	v_fmac_f32_e32 v150, v22, v143
	v_fmac_f32_e32 v151, v23, v143
	v_add_f32_e32 v144, v144, v146
	v_add_f32_e32 v145, v145, v147
	v_add_f32_e32 v148, v148, v150
	v_add_f32_e32 v149, v149, v151
	v_add_f32_e32 v144, v144, v148
	v_add_f32_e32 v145, v145, v149
	v_fma_f32 v152, -v17, v37, v144
	v_fma_f32 v153, v17, v36, v145
	v_fma_f32 v36, v16, v36, v152
	v_fma_f32 v37, v16, v37, v153
	ds_write_b32 v154, v36 offset:6864
	ds_write_b32 v154, v37 offset:7120
	ds_read_b128 v[128:131], v46 offset:9408
	ds_read_b128 v[132:135], v46 offset:9424
	ds_read_b128 v[136:139], v46 offset:9440
	ds_read_b128 v[140:143], v46 offset:9456
	s_waitcnt lgkmcnt(6)
	v_mul_f32_e32 v144, v12, v112
	v_mul_f32_e32 v145, v13, v112
	v_mul_f32_e32 v146, v4, v116
	v_mul_f32_e32 v147, v5, v116
	v_mul_f32_e32 v148, v32, v120
	v_mul_f32_e32 v149, v33, v120
	v_mul_f32_e32 v150, v24, v124
	v_mul_f32_e32 v151, v25, v124
	v_fmac_f32_e32 v144, v14, v113
	v_fmac_f32_e32 v145, v15, v113
	v_fmac_f32_e32 v146, v6, v117
	v_fmac_f32_e32 v147, v7, v117
	v_fmac_f32_e32 v148, v34, v121
	v_fmac_f32_e32 v149, v35, v121
	v_fmac_f32_e32 v150, v26, v125
	v_fmac_f32_e32 v151, v27, v125
	v_fmac_f32_e32 v144, v8, v114
	v_fmac_f32_e32 v145, v9, v114
	v_fmac_f32_e32 v146, v0, v118
	v_fmac_f32_e32 v147, v1, v118
	v_fmac_f32_e32 v148, v28, v122
	v_fmac_f32_e32 v149, v29, v122
	v_fmac_f32_e32 v150, v20, v126
	v_fmac_f32_e32 v151, v21, v126
	v_fmac_f32_e32 v144, v10, v115
	v_fmac_f32_e32 v145, v11, v115
	v_fmac_f32_e32 v146, v2, v119
	v_fmac_f32_e32 v147, v3, v119
	v_fmac_f32_e32 v148, v30, v123
	v_fmac_f32_e32 v149, v31, v123
	v_fmac_f32_e32 v150, v22, v127
	v_fmac_f32_e32 v151, v23, v127
	v_add_f32_e32 v144, v144, v146
	v_add_f32_e32 v145, v145, v147
	v_add_f32_e32 v148, v148, v150
	v_add_f32_e32 v149, v149, v151
	v_add_f32_e32 v144, v144, v148
	v_add_f32_e32 v145, v145, v149
	v_fma_f32 v152, -v17, v37, v144
	v_fma_f32 v153, v17, v36, v145
	v_fma_f32 v36, v16, v36, v152
	v_fma_f32 v37, v16, v37, v153
	ds_write_b32 v154, v36 offset:7392
	ds_write_b32 v154, v37 offset:7648
	s_waitcnt lgkmcnt(2)
; DI float sigm(float x) { return __builtin_amdgcn_rcpf(1.f + __expf(-x)); }
; template <bool FULL>
; DI void ssm_item(const P& p, int l, int item, char* smem) {
;     ...
;     for (int t = 0; t < 16; ++t) {
;       const float4* up = (const float4*)(us + t * 16);
;       const float4 u0 = up[0], u1 = up[1], u2 = up[2], u3 = up[3];
;       const float uu[16] = {u0.x, u0.y, u0.z, u0.w, u1.x, u1.y, u1.z, u1.w, u2.x, u2.y, u2.z, u2.w, u3.x, u3.y, u3.z, u3.w};
;       float br = 0.f, bi = 0.f;
; #pragma unroll
;       for (int i = 0; i < 16; ++i) { br = fmaf(bbr[i], uu[i], br); bi = fmaf(bbi[i], uu[i], bi); }
;       const float nhr = ar * hr - ai * hi + br, nhi = ar * hi + ai * hr + bi;
;       hr = nhr; hi = nhi;
;       if (FULL) { H[t * 132 + lane] = hr; H[t * 132 + 64 + lane] = hi; }
;     }
;     if (FULL) {
;       __builtin_amdgcn_wave_barrier();
;       f32x4 acc = {0.f, 0.f, 0.f, 0.f};
;       const float* hp = H + ch * 132 + quad * 32;
; #pragma unroll
;       for (int i = 0; i < 8; ++i) {
;         const float4 hv = *(const float4*)(hp + 4 * i);
;         acc = __builtin_amdgcn_mfma_f32_16x16x4f32(hv.x, creg[4 * i], acc, 0, 0, 0);
;         acc = __builtin_amdgcn_mfma_f32_16x16x4f32(hv.y, creg[4 * i + 1], acc, 0, 0, 0);
;         acc = __builtin_amdgcn_mfma_f32_16x16x4f32(hv.z, creg[4 * i + 2], acc, 0, 0, 0);
;         acc = __builtin_amdgcn_mfma_f32_16x16x4f32(hv.w, creg[4 * i + 3], acc, 0, 0, 0);
;       }
; #pragma unroll
;       for (int r = 0; r < 4; ++r) {
;         const int tl = quad * 4 + r;
;         float y = acc[r] + dsk * us[tl * 16 + ch];
;         const float y3 = y * y * y;
;         y = y * sigm(1.5957691216057308f * (y + 0.044715f * y3));
;         p.y_pre[(tok0 + s * 16 + tl) * 512 + g * 16 + ch] = f2bf(y);
;       }
	v_mul_f32_e32 v144, v12, v128
	v_mul_f32_e32 v145, v13, v128
	v_mul_f32_e32 v146, v4, v132
	v_mul_f32_e32 v147, v5, v132
	v_mul_f32_e32 v148, v32, v136
	v_mul_f32_e32 v149, v33, v136
	v_mul_f32_e32 v150, v24, v140
	v_mul_f32_e32 v151, v25, v140
	v_fmac_f32_e32 v144, v14, v129
	v_fmac_f32_e32 v145, v15, v129
	v_fmac_f32_e32 v146, v6, v133
	v_fmac_f32_e32 v147, v7, v133
	v_fmac_f32_e32 v148, v34, v137
	v_fmac_f32_e32 v149, v35, v137
	v_fmac_f32_e32 v150, v26, v141
	v_fmac_f32_e32 v151, v27, v141
	v_fmac_f32_e32 v144, v8, v130
	v_fmac_f32_e32 v145, v9, v130
	v_fmac_f32_e32 v146, v0, v134
	v_fmac_f32_e32 v147, v1, v134
	v_fmac_f32_e32 v148, v28, v138
	v_fmac_f32_e32 v149, v29, v138
	v_fmac_f32_e32 v150, v20, v142
	v_fmac_f32_e32 v151, v21, v142
	v_fmac_f32_e32 v144, v10, v131
	v_fmac_f32_e32 v145, v11, v131
	v_fmac_f32_e32 v146, v2, v135
	v_fmac_f32_e32 v147, v3, v135
	v_fmac_f32_e32 v148, v30, v139
	v_fmac_f32_e32 v149, v31, v139
	v_fmac_f32_e32 v150, v22, v143
	v_fmac_f32_e32 v151, v23, v143
	v_add_f32_e32 v144, v144, v146
	v_add_f32_e32 v145, v145, v147
	v_add_f32_e32 v148, v148, v150
	v_add_f32_e32 v149, v149, v151
	v_add_f32_e32 v144, v144, v148
	v_add_f32_e32 v145, v145, v149
	v_fma_f32 v152, -v17, v37, v144
	v_fma_f32 v153, v17, v36, v145
	v_fma_f32 v36, v16, v36, v152
	v_fma_f32 v37, v16, v37, v153
	ds_write_b32 v154, v36 offset:7920
	ds_write_b32 v154, v37 offset:8176
	ds_read_b128 v[92:95], v81
	ds_read_b128 v[96:99], v81 offset:16
	s_lshl_b32 s7, s7, 4
	v_lshrrev_b32_e32 v155, 2, v86
	v_and_b32_e32 v160, 15, v155
	v_lshlrev_b32_e32 v162, 1, v160
	v_lshrrev_b32_e32 v161, 4, v155
	v_lshl_add_u32 v163, v161, 7, v162
	v_add_u32_e32 v163, v46, v163
	v_lshl_add_u32 v164, v155, 4, v46
	v_and_b32_e32 v165, 1, v155
	v_lshlrev_b32_e32 v165, 4, v165
	v_sub_u32_e32 v168, v165, v162
	v_ashrrev_i32_e32 v169, 31, v168
	v_lshl_add_u64 v[168:169], v[42:43], 0, v[168:169]
	v_lshrrev_b32_e32 v170, 1, v155
	v_or_b32_e32 v170, s7, v170
	v_or_b32_e32 v170, s0, v170
	v_mov_b32_e32 v171, s1
	v_lshlrev_b64 v[170:171], 10, v[170:171]
	v_lshl_add_u64 v[168:169], v[168:169], 0, v[170:171]
	v_or_b32_e32 v104, s7, v84
	v_or_b32_e32 v109, s7, v85
	s_waitcnt lgkmcnt(1)
	v_mfma_f32_16x16x4_f32 v[100:103], v92, v47, 0
	s_cmp_eq_u32 s6, 8
	v_mfma_f32_16x16x4_f32 v[100:103], v93, v48, v[100:103]
	v_mfma_f32_16x16x4_f32 v[100:103], v94, v49, v[100:103]
	v_mfma_f32_16x16x4_f32 v[92:95], v95, v50, v[100:103]
	s_waitcnt lgkmcnt(0)
	v_mfma_f32_16x16x4_f32 v[92:95], v96, v51, v[92:95]
	v_mfma_f32_16x16x4_f32 v[92:95], v97, v52, v[92:95]
	v_mfma_f32_16x16x4_f32 v[92:95], v98, v53, v[92:95]
	v_mfma_f32_16x16x4_f32 v[92:95], v99, v54, v[92:95]
	ds_read_b128 v[96:99], v81 offset:32
	s_nop 2
	ds_read_b128 v[100:103], v81 offset:48
	s_waitcnt lgkmcnt(1)
	v_mfma_f32_16x16x4_f32 v[92:95], v96, v55, v[92:95]
	v_mfma_f32_16x16x4_f32 v[92:95], v97, v56, v[92:95]
	v_mfma_f32_16x16x4_f32 v[92:95], v98, v57, v[92:95]
	v_mfma_f32_16x16x4_f32 v[92:95], v99, v58, v[92:95]
	s_waitcnt lgkmcnt(0)
	v_mfma_f32_16x16x4_f32 v[92:95], v100, v59, v[92:95]
	v_mfma_f32_16x16x4_f32 v[92:95], v101, v60, v[92:95]
	v_mfma_f32_16x16x4_f32 v[92:95], v102, v61, v[92:95]
	v_mfma_f32_16x16x4_f32 v[92:95], v103, v62, v[92:95]
	ds_read_b128 v[96:99], v81 offset:64
	ds_read_b128 v[100:103], v81 offset:80
	s_waitcnt lgkmcnt(1)
	v_mfma_f32_16x16x4_f32 v[92:95], v96, v63, v[92:95]
	v_mfma_f32_16x16x4_f32 v[92:95], v97, v64, v[92:95]
	v_mfma_f32_16x16x4_f32 v[92:95], v98, v65, v[92:95]
	v_mfma_f32_16x16x4_f32 v[92:95], v99, v66, v[92:95]
	s_waitcnt lgkmcnt(0)
	v_mfma_f32_16x16x4_f32 v[92:95], v100, v67, v[92:95]
	v_mfma_f32_16x16x4_f32 v[92:95], v101, v68, v[92:95]
	v_mfma_f32_16x16x4_f32 v[92:95], v102, v69, v[92:95]
	v_mfma_f32_16x16x4_f32 v[92:95], v103, v70, v[92:95]
	ds_read_b128 v[96:99], v81 offset:96
	ds_read_b128 v[100:103], v81 offset:112
	ds_read_b32 v91, v87 offset:8448
	ds_read_b32 v106, v88 offset:8448
	ds_read_b32 v107, v89 offset:8448
	ds_read_b32 v108, v90 offset:8448
	s_waitcnt lgkmcnt(5)
	v_mfma_f32_16x16x4_f32 v[92:95], v96, v71, v[92:95]
	v_or_b32_e32 v96, s7, v82
	v_or_b32_e32 v96, s0, v96
	v_mfma_f32_16x16x4_f32 v[92:95], v97, v72, v[92:95]
	v_mov_b32_e32 v97, s1
	v_mfma_f32_16x16x4_f32 v[92:95], v98, v73, v[92:95]
	v_mfma_f32_16x16x4_f32 v[92:95], v99, v74, v[92:95]
	v_lshlrev_b64 v[98:99], 10, v[96:97]
	v_lshl_add_u64 v[98:99], v[42:43], 0, v[98:99]
	s_waitcnt lgkmcnt(4)
	v_mfma_f32_16x16x4_f32 v[92:95], v100, v75, v[92:95]
	v_or_b32_e32 v100, s7, v83
	v_or_b32_e32 v96, s0, v100
	s_mov_b32 s7, s6
	v_mfma_f32_16x16x4_f32 v[92:95], v101, v76, v[92:95]
	v_lshlrev_b64 v[100:101], 10, v[96:97]
	v_or_b32_e32 v96, s0, v104
	v_lshlrev_b64 v[104:105], 10, v[96:97]
	v_or_b32_e32 v96, s0, v109
	v_lshlrev_b64 v[96:97], 10, v[96:97]
	v_lshl_add_u64 v[100:101], v[42:43], 0, v[100:101]
	v_lshl_add_u64 v[104:105], v[42:43], 0, v[104:105]
	v_mfma_f32_16x16x4_f32 v[92:95], v102, v77, v[92:95]
	v_lshl_add_u64 v[96:97], v[42:43], 0, v[96:97]
	v_mfma_f32_16x16x4_f32 v[92:95], v103, v78, v[92:95]
	s_waitcnt lgkmcnt(3)
	s_nop 8
	v_fma_f32 v91, v79, v91, v92
	s_waitcnt lgkmcnt(2)
	v_fma_f32 v92, v79, v106, v93
	s_waitcnt lgkmcnt(1)
	v_fma_f32 v93, v79, v107, v94
	s_waitcnt lgkmcnt(0)
	v_fmac_f32_e32 v95, v79, v108
	v_mul_f32_e32 v94, v91, v91
	v_mul_f32_e32 v102, v92, v92
	v_mul_f32_e32 v103, v93, v93
	v_mul_f32_e32 v106, v95, v95
	v_mul_f32_e32 v94, v91, v94
	v_mul_f32_e32 v102, v92, v102
	v_mul_f32_e32 v103, v93, v103
	v_mul_f32_e32 v106, v95, v106
	v_fmamk_f32 v94, v94, 0x3d372713, v91
	v_fmamk_f32 v102, v102, 0x3d372713, v92
	v_fmamk_f32 v103, v103, 0x3d372713, v93
	v_fmamk_f32 v106, v106, 0x3d372713, v95
	v_mul_f32_e32 v94, 0x3fcc422a, v94
	v_mul_f32_e32 v102, 0x3fcc422a, v102
	v_mul_f32_e32 v103, 0x3fcc422a, v103
	v_mul_f32_e32 v106, 0x3fcc422a, v106
	v_mul_f32_e32 v94, 0xbfb8aa3b, v94
	v_mul_f32_e32 v102, 0xbfb8aa3b, v102
	v_mul_f32_e32 v103, 0xbfb8aa3b, v103
	v_mul_f32_e32 v106, 0xbfb8aa3b, v106
	v_exp_f32_e32 v94, v94
	v_exp_f32_e32 v102, v102
	v_exp_f32_e32 v103, v103
	v_exp_f32_e32 v106, v106
	v_add_f32_e32 v94, 1.0, v94
	v_add_f32_e32 v102, 1.0, v102
	v_add_f32_e32 v103, 1.0, v103
	v_add_f32_e32 v106, 1.0, v106
	v_rcp_f32_e32 v94, v94
	v_rcp_f32_e32 v102, v102
	v_rcp_f32_e32 v103, v103
	v_rcp_f32_e32 v106, v106
	v_mul_f32_e32 v91, v91, v94
	v_mul_f32_e32 v92, v92, v102
	v_mul_f32_e32 v93, v93, v103
	v_mul_f32_e32 v94, v95, v106
	v_cvt_pk_bf16_f32 v91, v91, s0
	v_cvt_pk_bf16_f32 v92, v92, s0
	v_cvt_pk_bf16_f32 v93, v93, s0
	v_cvt_pk_bf16_f32 v94, v94, s0
	ds_write_b16 v163, v91
	ds_write_b16 v163, v92 offset:32
	ds_write_b16 v163, v93 offset:64
	ds_write_b16 v163, v94 offset:96
	ds_read_b128 v[156:159], v164
	s_mov_b64 s[8:9], exec
	s_mov_b32 exec_lo, -1
	s_mov_b32 exec_hi, 0
	s_waitcnt lgkmcnt(0)
	global_store_dwordx4 v[168:169], v[156:159], off
	s_mov_b64 exec, s[8:9]
	s_cbranch_scc0 .LBB0_170
	v_readlane_b32 s0, v249, 5
	s_add_i32 s21, s21, s0
	v_readlane_b32 s0, v250, 62
	s_add_i32 s20, s20, s0
	s_cmpk_gt_i32 s21, 0xfff
	v_readlane_b32 s1, v249, 6
	s_cbranch_scc0 .LBB0_165

; template <bool FULL>
; DI void ssm_item(const P& p, int l, int item, char* smem) {
;     ...
; #pragma unroll 4
;     for (int t = 0; t < 16; ++t) {
;       const float4* up = (const float4*)(us + t * 16);
;       const float4 u0 = up[0], u1 = up[1], u2 = up[2], u3 = up[3];
;       const float uu[16] = {u0.x, u0.y, u0.z, u0.w, u1.x, u1.y, u1.z, u1.w, u2.x, u2.y, u2.z, u2.w, u3.x, u3.y, u3.z, u3.w};
;       float br = 0.f, bi = 0.f;
; #pragma unroll
;       for (int i = 0; i < 16; ++i) { br = fmaf(bbr[i], uu[i], br); bi = fmaf(bbi[i], uu[i], bi); }
;       const float nhr = ar * hr - ai * hi + br, nhi = ar * hi + ai * hr + bi;
;       hr = nhr; hi = nhi;
.LBB0_358:
	ds_read_b128 v[70:73], v47
	ds_read_b128 v[74:77], v47 offset:16
	ds_read_b128 v[78:81], v47 offset:32
	ds_read_b128 v[82:85], v47 offset:48
	ds_read_b128 v[86:89], v47 offset:64
	ds_read_b128 v[90:93], v47 offset:80
	ds_read_b128 v[94:97], v47 offset:96
	ds_read_b128 v[98:101], v47 offset:112
	s_waitcnt lgkmcnt(4)
	v_mul_f32_e32 v102, v12, v70
	v_mul_f32_e32 v103, v13, v70
	v_mul_f32_e32 v104, v4, v74
	v_mul_f32_e32 v105, v5, v74
	v_mul_f32_e32 v106, v28, v78
	v_mul_f32_e32 v107, v29, v78
	v_mul_f32_e32 v108, v20, v82
	v_mul_f32_e32 v109, v21, v82
	v_fmac_f32_e32 v102, v14, v71
	v_fmac_f32_e32 v103, v15, v71
	v_fmac_f32_e32 v104, v6, v75
	v_fmac_f32_e32 v105, v7, v75
	v_fmac_f32_e32 v106, v30, v79
	v_fmac_f32_e32 v107, v31, v79
	v_fmac_f32_e32 v108, v22, v83
	v_fmac_f32_e32 v109, v23, v83
	v_fmac_f32_e32 v102, v8, v72
	v_fmac_f32_e32 v103, v9, v72
	v_fmac_f32_e32 v104, v0, v76
	v_fmac_f32_e32 v105, v1, v76
	v_fmac_f32_e32 v106, v24, v80
	v_fmac_f32_e32 v107, v25, v80
	v_fmac_f32_e32 v108, v16, v84
	v_fmac_f32_e32 v109, v17, v84
	v_fmac_f32_e32 v102, v10, v73
	v_fmac_f32_e32 v103, v11, v73
	v_fmac_f32_e32 v104, v2, v77
	v_fmac_f32_e32 v105, v3, v77
	v_fmac_f32_e32 v106, v26, v81
	v_fmac_f32_e32 v107, v27, v81
	v_fmac_f32_e32 v108, v18, v85
	v_fmac_f32_e32 v109, v19, v85
	v_add_f32_e32 v102, v102, v104
	v_add_f32_e32 v103, v103, v105
	v_add_f32_e32 v106, v106, v108
	v_add_f32_e32 v107, v107, v109
	v_add_f32_e32 v102, v102, v106
	v_add_f32_e32 v103, v103, v107
	v_fma_f32 v110, -v35, v45, v102
	v_fma_f32 v111, v35, v44, v103
	v_fma_f32 v44, v34, v44, v110
	v_fma_f32 v45, v34, v45, v111
	ds_read_b128 v[70:73], v47 offset:128
	ds_read_b128 v[74:77], v47 offset:144
	ds_read_b128 v[78:81], v47 offset:160
	ds_read_b128 v[82:85], v47 offset:176
	s_waitcnt lgkmcnt(4)
	v_mul_f32_e32 v102, v12, v86
	v_mul_f32_e32 v103, v13, v86
	v_mul_f32_e32 v104, v4, v90
	v_mul_f32_e32 v105, v5, v90
	v_mul_f32_e32 v106, v28, v94
	v_mul_f32_e32 v107, v29, v94
	v_mul_f32_e32 v108, v20, v98
	v_mul_f32_e32 v109, v21, v98
	v_fmac_f32_e32 v102, v14, v87
	v_fmac_f32_e32 v103, v15, v87
	v_fmac_f32_e32 v104, v6, v91
	v_fmac_f32_e32 v105, v7, v91
	v_fmac_f32_e32 v106, v30, v95
	v_fmac_f32_e32 v107, v31, v95
	v_fmac_f32_e32 v108, v22, v99
	v_fmac_f32_e32 v109, v23, v99
	v_fmac_f32_e32 v102, v8, v88
	v_fmac_f32_e32 v103, v9, v88
	v_fmac_f32_e32 v104, v0, v92
	v_fmac_f32_e32 v105, v1, v92
	v_fmac_f32_e32 v106, v24, v96
	v_fmac_f32_e32 v107, v25, v96
	v_fmac_f32_e32 v108, v16, v100
	v_fmac_f32_e32 v109, v17, v100
	v_fmac_f32_e32 v102, v10, v89
	v_fmac_f32_e32 v103, v11, v89
	v_fmac_f32_e32 v104, v2, v93
	v_fmac_f32_e32 v105, v3, v93
	v_fmac_f32_e32 v106, v26, v97
	v_fmac_f32_e32 v107, v27, v97
	v_fmac_f32_e32 v108, v18, v101
	v_fmac_f32_e32 v109, v19, v101
	v_add_f32_e32 v102, v102, v104
	v_add_f32_e32 v103, v103, v105
	v_add_f32_e32 v106, v106, v108
	v_add_f32_e32 v107, v107, v109
	v_add_f32_e32 v102, v102, v106
	v_add_f32_e32 v103, v103, v107
	v_fma_f32 v110, -v35, v45, v102
	v_fma_f32 v111, v35, v44, v103
	v_fma_f32 v44, v34, v44, v110
	v_fma_f32 v45, v34, v45, v111
	ds_read_b128 v[86:89], v47 offset:192
	ds_read_b128 v[90:93], v47 offset:208
	ds_read_b128 v[94:97], v47 offset:224
	ds_read_b128 v[98:101], v47 offset:240
	s_waitcnt lgkmcnt(4)
	v_mul_f32_e32 v102, v12, v70
	v_mul_f32_e32 v103, v13, v70
	v_mul_f32_e32 v104, v4, v74
	v_mul_f32_e32 v105, v5, v74
	v_mul_f32_e32 v106, v28, v78
	v_mul_f32_e32 v107, v29, v78
	v_mul_f32_e32 v108, v20, v82
	v_mul_f32_e32 v109, v21, v82
	v_fmac_f32_e32 v102, v14, v71
	v_fmac_f32_e32 v103, v15, v71
	v_fmac_f32_e32 v104, v6, v75
	v_fmac_f32_e32 v105, v7, v75
	v_fmac_f32_e32 v106, v30, v79
	v_fmac_f32_e32 v107, v31, v79
	v_fmac_f32_e32 v108, v22, v83
	v_fmac_f32_e32 v109, v23, v83
	v_fmac_f32_e32 v102, v8, v72
	v_fmac_f32_e32 v103, v9, v72
	v_fmac_f32_e32 v104, v0, v76
	v_fmac_f32_e32 v105, v1, v76
	v_fmac_f32_e32 v106, v24, v80
	v_fmac_f32_e32 v107, v25, v80
	v_fmac_f32_e32 v108, v16, v84
	v_fmac_f32_e32 v109, v17, v84
	v_fmac_f32_e32 v102, v10, v73
	v_fmac_f32_e32 v103, v11, v73
	v_fmac_f32_e32 v104, v2, v77
	v_fmac_f32_e32 v105, v3, v77
	v_fmac_f32_e32 v106, v26, v81
	v_fmac_f32_e32 v107, v27, v81
	v_fmac_f32_e32 v108, v18, v85
	v_fmac_f32_e32 v109, v19, v85
	v_add_f32_e32 v102, v102, v104
	v_add_f32_e32 v103, v103, v105
	v_add_f32_e32 v106, v106, v108
	v_add_f32_e32 v107, v107, v109
	v_add_f32_e32 v102, v102, v106
	v_add_f32_e32 v103, v103, v107
	v_fma_f32 v110, -v35, v45, v102
	v_fma_f32 v111, v35, v44, v103
	v_fma_f32 v44, v34, v44, v110
	v_fma_f32 v45, v34, v45, v111
	ds_read_b128 v[70:73], v47 offset:256
	ds_read_b128 v[74:77], v47 offset:272
	ds_read_b128 v[78:81], v47 offset:288
	ds_read_b128 v[82:85], v47 offset:304
	s_waitcnt lgkmcnt(4)
	v_mul_f32_e32 v102, v12, v86
	v_mul_f32_e32 v103, v13, v86
	v_mul_f32_e32 v104, v4, v90
	v_mul_f32_e32 v105, v5, v90
	v_mul_f32_e32 v106, v28, v94
	v_mul_f32_e32 v107, v29, v94
	v_mul_f32_e32 v108, v20, v98
	v_mul_f32_e32 v109, v21, v98
	v_fmac_f32_e32 v102, v14, v87
	v_fmac_f32_e32 v103, v15, v87
	v_fmac_f32_e32 v104, v6, v91
	v_fmac_f32_e32 v105, v7, v91
	v_fmac_f32_e32 v106, v30, v95
	v_fmac_f32_e32 v107, v31, v95
	v_fmac_f32_e32 v108, v22, v99
	v_fmac_f32_e32 v109, v23, v99
	v_fmac_f32_e32 v102, v8, v88
	v_fmac_f32_e32 v103, v9, v88
	v_fmac_f32_e32 v104, v0, v92
	v_fmac_f32_e32 v105, v1, v92
	v_fmac_f32_e32 v106, v24, v96
	v_fmac_f32_e32 v107, v25, v96
	v_fmac_f32_e32 v108, v16, v100
	v_fmac_f32_e32 v109, v17, v100
	v_fmac_f32_e32 v102, v10, v89
	v_fmac_f32_e32 v103, v11, v89
	v_fmac_f32_e32 v104, v2, v93
	v_fmac_f32_e32 v105, v3, v93
	v_fmac_f32_e32 v106, v26, v97
	v_fmac_f32_e32 v107, v27, v97
	v_fmac_f32_e32 v108, v18, v101
	v_fmac_f32_e32 v109, v19, v101
	v_add_f32_e32 v102, v102, v104
	v_add_f32_e32 v103, v103, v105
	v_add_f32_e32 v106, v106, v108
	v_add_f32_e32 v107, v107, v109
	v_add_f32_e32 v102, v102, v106
	v_add_f32_e32 v103, v103, v107
	v_fma_f32 v110, -v35, v45, v102
	v_fma_f32 v111, v35, v44, v103
	v_fma_f32 v44, v34, v44, v110
	v_fma_f32 v45, v34, v45, v111
	ds_read_b128 v[86:89], v47 offset:320
	ds_read_b128 v[90:93], v47 offset:336
	ds_read_b128 v[94:97], v47 offset:352
	ds_read_b128 v[98:101], v47 offset:368
	s_waitcnt lgkmcnt(4)
; template <bool FULL>
; DI void ssm_item(const P& p, int l, int item, char* smem) {
;     ...
;     for (int t = 0; t < 16; ++t) {
;       const float4* up = (const float4*)(us + t * 16);
;       const float4 u0 = up[0], u1 = up[1], u2 = up[2], u3 = up[3];
;       const float uu[16] = {u0.x, u0.y, u0.z, u0.w, u1.x, u1.y, u1.z, u1.w, u2.x, u2.y, u2.z, u2.w, u3.x, u3.y, u3.z, u3.w};
;       float br = 0.f, bi = 0.f;
; #pragma unroll
;       for (int i = 0; i < 16; ++i) { br = fmaf(bbr[i], uu[i], br); bi = fmaf(bbi[i], uu[i], bi); }
;       const float nhr = ar * hr - ai * hi + br, nhi = ar * hi + ai * hr + bi;
;       hr = nhr; hi = nhi;
	v_mul_f32_e32 v102, v12, v70
	v_mul_f32_e32 v103, v13, v70
	v_mul_f32_e32 v104, v4, v74
	v_mul_f32_e32 v105, v5, v74
	v_mul_f32_e32 v106, v28, v78
	v_mul_f32_e32 v107, v29, v78
	v_mul_f32_e32 v108, v20, v82
	v_mul_f32_e32 v109, v21, v82
	v_fmac_f32_e32 v102, v14, v71
	v_fmac_f32_e32 v103, v15, v71
	v_fmac_f32_e32 v104, v6, v75
	v_fmac_f32_e32 v105, v7, v75
	v_fmac_f32_e32 v106, v30, v79
	v_fmac_f32_e32 v107, v31, v79
	v_fmac_f32_e32 v108, v22, v83
	v_fmac_f32_e32 v109, v23, v83
	v_fmac_f32_e32 v102, v8, v72
	v_fmac_f32_e32 v103, v9, v72
	v_fmac_f32_e32 v104, v0, v76
	v_fmac_f32_e32 v105, v1, v76
	v_fmac_f32_e32 v106, v24, v80
	v_fmac_f32_e32 v107, v25, v80
	v_fmac_f32_e32 v108, v16, v84
	v_fmac_f32_e32 v109, v17, v84
	v_fmac_f32_e32 v102, v10, v73
	v_fmac_f32_e32 v103, v11, v73
	v_fmac_f32_e32 v104, v2, v77
	v_fmac_f32_e32 v105, v3, v77
	v_fmac_f32_e32 v106, v26, v81
	v_fmac_f32_e32 v107, v27, v81
	v_fmac_f32_e32 v108, v18, v85
	v_fmac_f32_e32 v109, v19, v85
	v_add_f32_e32 v102, v102, v104
	v_add_f32_e32 v103, v103, v105
	v_add_f32_e32 v106, v106, v108
	v_add_f32_e32 v107, v107, v109
	v_add_f32_e32 v102, v102, v106
	v_add_f32_e32 v103, v103, v107
	v_fma_f32 v110, -v35, v45, v102
	v_fma_f32 v111, v35, v44, v103
	v_fma_f32 v44, v34, v44, v110
	v_fma_f32 v45, v34, v45, v111
	ds_read_b128 v[70:73], v47 offset:384
	ds_read_b128 v[74:77], v47 offset:400
	ds_read_b128 v[78:81], v47 offset:416
	ds_read_b128 v[82:85], v47 offset:432
	s_waitcnt lgkmcnt(4)
	v_mul_f32_e32 v102, v12, v86
	v_mul_f32_e32 v103, v13, v86
	v_mul_f32_e32 v104, v4, v90
	v_mul_f32_e32 v105, v5, v90
	v_mul_f32_e32 v106, v28, v94
	v_mul_f32_e32 v107, v29, v94
	v_mul_f32_e32 v108, v20, v98
	v_mul_f32_e32 v109, v21, v98
	v_fmac_f32_e32 v102, v14, v87
	v_fmac_f32_e32 v103, v15, v87
	v_fmac_f32_e32 v104, v6, v91
	v_fmac_f32_e32 v105, v7, v91
	v_fmac_f32_e32 v106, v30, v95
	v_fmac_f32_e32 v107, v31, v95
	v_fmac_f32_e32 v108, v22, v99
	v_fmac_f32_e32 v109, v23, v99
	v_fmac_f32_e32 v102, v8, v88
	v_fmac_f32_e32 v103, v9, v88
	v_fmac_f32_e32 v104, v0, v92
	v_fmac_f32_e32 v105, v1, v92
	v_fmac_f32_e32 v106, v24, v96
	v_fmac_f32_e32 v107, v25, v96
	v_fmac_f32_e32 v108, v16, v100
	v_fmac_f32_e32 v109, v17, v100
	v_fmac_f32_e32 v102, v10, v89
	v_fmac_f32_e32 v103, v11, v89
	v_fmac_f32_e32 v104, v2, v93
	v_fmac_f32_e32 v105, v3, v93
	v_fmac_f32_e32 v106, v26, v97
	v_fmac_f32_e32 v107, v27, v97
	v_fmac_f32_e32 v108, v18, v101
	v_fmac_f32_e32 v109, v19, v101
	v_add_f32_e32 v102, v102, v104
	v_add_f32_e32 v103, v103, v105
	v_add_f32_e32 v106, v106, v108
	v_add_f32_e32 v107, v107, v109
	v_add_f32_e32 v102, v102, v106
	v_add_f32_e32 v103, v103, v107
	v_fma_f32 v110, -v35, v45, v102
	v_fma_f32 v111, v35, v44, v103
	v_fma_f32 v44, v34, v44, v110
	v_fma_f32 v45, v34, v45, v111
	ds_read_b128 v[86:89], v47 offset:448
	ds_read_b128 v[90:93], v47 offset:464
	ds_read_b128 v[94:97], v47 offset:480
	ds_read_b128 v[98:101], v47 offset:496
	s_waitcnt lgkmcnt(4)
	v_mul_f32_e32 v102, v12, v70
	v_mul_f32_e32 v103, v13, v70
	v_mul_f32_e32 v104, v4, v74
	v_mul_f32_e32 v105, v5, v74
	v_mul_f32_e32 v106, v28, v78
	v_mul_f32_e32 v107, v29, v78
	v_mul_f32_e32 v108, v20, v82
	v_mul_f32_e32 v109, v21, v82
	v_fmac_f32_e32 v102, v14, v71
	v_fmac_f32_e32 v103, v15, v71
	v_fmac_f32_e32 v104, v6, v75
	v_fmac_f32_e32 v105, v7, v75
	v_fmac_f32_e32 v106, v30, v79
	v_fmac_f32_e32 v107, v31, v79
	v_fmac_f32_e32 v108, v22, v83
	v_fmac_f32_e32 v109, v23, v83
	v_fmac_f32_e32 v102, v8, v72
	v_fmac_f32_e32 v103, v9, v72
	v_fmac_f32_e32 v104, v0, v76
	v_fmac_f32_e32 v105, v1, v76
	v_fmac_f32_e32 v106, v24, v80
	v_fmac_f32_e32 v107, v25, v80
	v_fmac_f32_e32 v108, v16, v84
	v_fmac_f32_e32 v109, v17, v84
	v_fmac_f32_e32 v102, v10, v73
	v_fmac_f32_e32 v103, v11, v73
	v_fmac_f32_e32 v104, v2, v77
	v_fmac_f32_e32 v105, v3, v77
	v_fmac_f32_e32 v106, v26, v81
	v_fmac_f32_e32 v107, v27, v81
	v_fmac_f32_e32 v108, v18, v85
	v_fmac_f32_e32 v109, v19, v85
	v_add_f32_e32 v102, v102, v104
	v_add_f32_e32 v103, v103, v105
	v_add_f32_e32 v106, v106, v108
	v_add_f32_e32 v107, v107, v109
	v_add_f32_e32 v102, v102, v106
	v_add_f32_e32 v103, v103, v107
	v_fma_f32 v110, -v35, v45, v102
	v_fma_f32 v111, v35, v44, v103
	v_fma_f32 v44, v34, v44, v110
	v_fma_f32 v45, v34, v45, v111
	ds_read_b128 v[70:73], v47 offset:512
	ds_read_b128 v[74:77], v47 offset:528
	ds_read_b128 v[78:81], v47 offset:544
	ds_read_b128 v[82:85], v47 offset:560
	s_waitcnt lgkmcnt(4)
	v_mul_f32_e32 v102, v12, v86
	v_mul_f32_e32 v103, v13, v86
	v_mul_f32_e32 v104, v4, v90
	v_mul_f32_e32 v105, v5, v90
	v_mul_f32_e32 v106, v28, v94
	v_mul_f32_e32 v107, v29, v94
	v_mul_f32_e32 v108, v20, v98
	v_mul_f32_e32 v109, v21, v98
	v_fmac_f32_e32 v102, v14, v87
	v_fmac_f32_e32 v103, v15, v87
	v_fmac_f32_e32 v104, v6, v91
	v_fmac_f32_e32 v105, v7, v91
	v_fmac_f32_e32 v106, v30, v95
	v_fmac_f32_e32 v107, v31, v95
	v_fmac_f32_e32 v108, v22, v99
	v_fmac_f32_e32 v109, v23, v99
	v_fmac_f32_e32 v102, v8, v88
	v_fmac_f32_e32 v103, v9, v88
	v_fmac_f32_e32 v104, v0, v92
	v_fmac_f32_e32 v105, v1, v92
	v_fmac_f32_e32 v106, v24, v96
	v_fmac_f32_e32 v107, v25, v96
	v_fmac_f32_e32 v108, v16, v100
	v_fmac_f32_e32 v109, v17, v100
	v_fmac_f32_e32 v102, v10, v89
	v_fmac_f32_e32 v103, v11, v89
	v_fmac_f32_e32 v104, v2, v93
	v_fmac_f32_e32 v105, v3, v93
	v_fmac_f32_e32 v106, v26, v97
	v_fmac_f32_e32 v107, v27, v97
	v_fmac_f32_e32 v108, v18, v101
	v_fmac_f32_e32 v109, v19, v101
	v_add_f32_e32 v102, v102, v104
	v_add_f32_e32 v103, v103, v105
	v_add_f32_e32 v106, v106, v108
	v_add_f32_e32 v107, v107, v109
	v_add_f32_e32 v102, v102, v106
	v_add_f32_e32 v103, v103, v107
	v_fma_f32 v110, -v35, v45, v102
	v_fma_f32 v111, v35, v44, v103
	v_fma_f32 v44, v34, v44, v110
	v_fma_f32 v45, v34, v45, v111
	ds_read_b128 v[86:89], v47 offset:576
	ds_read_b128 v[90:93], v47 offset:592
	ds_read_b128 v[94:97], v47 offset:608
	ds_read_b128 v[98:101], v47 offset:624
	s_waitcnt lgkmcnt(4)
; template <bool FULL>
; DI void ssm_item(const P& p, int l, int item, char* smem) {
;     ...
;     for (int t = 0; t < 16; ++t) {
;       const float4* up = (const float4*)(us + t * 16);
;       const float4 u0 = up[0], u1 = up[1], u2 = up[2], u3 = up[3];
;       const float uu[16] = {u0.x, u0.y, u0.z, u0.w, u1.x, u1.y, u1.z, u1.w, u2.x, u2.y, u2.z, u2.w, u3.x, u3.y, u3.z, u3.w};
;       float br = 0.f, bi = 0.f;
; #pragma unroll
;       for (int i = 0; i < 16; ++i) { br = fmaf(bbr[i], uu[i], br); bi = fmaf(bbi[i], uu[i], bi); }
;       const float nhr = ar * hr - ai * hi + br, nhi = ar * hi + ai * hr + bi;
;       hr = nhr; hi = nhi;
	v_mul_f32_e32 v102, v12, v70
	v_mul_f32_e32 v103, v13, v70
	v_mul_f32_e32 v104, v4, v74
	v_mul_f32_e32 v105, v5, v74
	v_mul_f32_e32 v106, v28, v78
	v_mul_f32_e32 v107, v29, v78
	v_mul_f32_e32 v108, v20, v82
	v_mul_f32_e32 v109, v21, v82
	v_fmac_f32_e32 v102, v14, v71
	v_fmac_f32_e32 v103, v15, v71
	v_fmac_f32_e32 v104, v6, v75
	v_fmac_f32_e32 v105, v7, v75
	v_fmac_f32_e32 v106, v30, v79
	v_fmac_f32_e32 v107, v31, v79
	v_fmac_f32_e32 v108, v22, v83
	v_fmac_f32_e32 v109, v23, v83
	v_fmac_f32_e32 v102, v8, v72
	v_fmac_f32_e32 v103, v9, v72
	v_fmac_f32_e32 v104, v0, v76
	v_fmac_f32_e32 v105, v1, v76
	v_fmac_f32_e32 v106, v24, v80
	v_fmac_f32_e32 v107, v25, v80
	v_fmac_f32_e32 v108, v16, v84
	v_fmac_f32_e32 v109, v17, v84
	v_fmac_f32_e32 v102, v10, v73
	v_fmac_f32_e32 v103, v11, v73
	v_fmac_f32_e32 v104, v2, v77
	v_fmac_f32_e32 v105, v3, v77
	v_fmac_f32_e32 v106, v26, v81
	v_fmac_f32_e32 v107, v27, v81
	v_fmac_f32_e32 v108, v18, v85
	v_fmac_f32_e32 v109, v19, v85
	v_add_f32_e32 v102, v102, v104
	v_add_f32_e32 v103, v103, v105
	v_add_f32_e32 v106, v106, v108
	v_add_f32_e32 v107, v107, v109
	v_add_f32_e32 v102, v102, v106
	v_add_f32_e32 v103, v103, v107
	v_fma_f32 v110, -v35, v45, v102
	v_fma_f32 v111, v35, v44, v103
	v_fma_f32 v44, v34, v44, v110
	v_fma_f32 v45, v34, v45, v111
	ds_read_b128 v[70:73], v47 offset:640
	ds_read_b128 v[74:77], v47 offset:656
	ds_read_b128 v[78:81], v47 offset:672
	ds_read_b128 v[82:85], v47 offset:688
	s_waitcnt lgkmcnt(4)
	v_mul_f32_e32 v102, v12, v86
	v_mul_f32_e32 v103, v13, v86
	v_mul_f32_e32 v104, v4, v90
	v_mul_f32_e32 v105, v5, v90
	v_mul_f32_e32 v106, v28, v94
	v_mul_f32_e32 v107, v29, v94
	v_mul_f32_e32 v108, v20, v98
	v_mul_f32_e32 v109, v21, v98
	v_fmac_f32_e32 v102, v14, v87
	v_fmac_f32_e32 v103, v15, v87
	v_fmac_f32_e32 v104, v6, v91
	v_fmac_f32_e32 v105, v7, v91
	v_fmac_f32_e32 v106, v30, v95
	v_fmac_f32_e32 v107, v31, v95
	v_fmac_f32_e32 v108, v22, v99
	v_fmac_f32_e32 v109, v23, v99
	v_fmac_f32_e32 v102, v8, v88
	v_fmac_f32_e32 v103, v9, v88
	v_fmac_f32_e32 v104, v0, v92
	v_fmac_f32_e32 v105, v1, v92
	v_fmac_f32_e32 v106, v24, v96
	v_fmac_f32_e32 v107, v25, v96
	v_fmac_f32_e32 v108, v16, v100
	v_fmac_f32_e32 v109, v17, v100
	v_fmac_f32_e32 v102, v10, v89
	v_fmac_f32_e32 v103, v11, v89
	v_fmac_f32_e32 v104, v2, v93
	v_fmac_f32_e32 v105, v3, v93
	v_fmac_f32_e32 v106, v26, v97
	v_fmac_f32_e32 v107, v27, v97
	v_fmac_f32_e32 v108, v18, v101
	v_fmac_f32_e32 v109, v19, v101
	v_add_f32_e32 v102, v102, v104
	v_add_f32_e32 v103, v103, v105
	v_add_f32_e32 v106, v106, v108
	v_add_f32_e32 v107, v107, v109
	v_add_f32_e32 v102, v102, v106
	v_add_f32_e32 v103, v103, v107
	v_fma_f32 v110, -v35, v45, v102
	v_fma_f32 v111, v35, v44, v103
	v_fma_f32 v44, v34, v44, v110
	v_fma_f32 v45, v34, v45, v111
	ds_read_b128 v[86:89], v47 offset:704
	ds_read_b128 v[90:93], v47 offset:720
	ds_read_b128 v[94:97], v47 offset:736
	ds_read_b128 v[98:101], v47 offset:752
	s_waitcnt lgkmcnt(4)
	v_mul_f32_e32 v102, v12, v70
	v_mul_f32_e32 v103, v13, v70
	v_mul_f32_e32 v104, v4, v74
	v_mul_f32_e32 v105, v5, v74
	v_mul_f32_e32 v106, v28, v78
	v_mul_f32_e32 v107, v29, v78
	v_mul_f32_e32 v108, v20, v82
	v_mul_f32_e32 v109, v21, v82
	v_fmac_f32_e32 v102, v14, v71
	v_fmac_f32_e32 v103, v15, v71
	v_fmac_f32_e32 v104, v6, v75
	v_fmac_f32_e32 v105, v7, v75
	v_fmac_f32_e32 v106, v30, v79
	v_fmac_f32_e32 v107, v31, v79
	v_fmac_f32_e32 v108, v22, v83
	v_fmac_f32_e32 v109, v23, v83
	v_fmac_f32_e32 v102, v8, v72
	v_fmac_f32_e32 v103, v9, v72
	v_fmac_f32_e32 v104, v0, v76
	v_fmac_f32_e32 v105, v1, v76
	v_fmac_f32_e32 v106, v24, v80
	v_fmac_f32_e32 v107, v25, v80
	v_fmac_f32_e32 v108, v16, v84
	v_fmac_f32_e32 v109, v17, v84
	v_fmac_f32_e32 v102, v10, v73
	v_fmac_f32_e32 v103, v11, v73
	v_fmac_f32_e32 v104, v2, v77
	v_fmac_f32_e32 v105, v3, v77
	v_fmac_f32_e32 v106, v26, v81
	v_fmac_f32_e32 v107, v27, v81
	v_fmac_f32_e32 v108, v18, v85
	v_fmac_f32_e32 v109, v19, v85
	v_add_f32_e32 v102, v102, v104
	v_add_f32_e32 v103, v103, v105
	v_add_f32_e32 v106, v106, v108
	v_add_f32_e32 v107, v107, v109
	v_add_f32_e32 v102, v102, v106
	v_add_f32_e32 v103, v103, v107
	v_fma_f32 v110, -v35, v45, v102
	v_fma_f32 v111, v35, v44, v103
	v_fma_f32 v44, v34, v44, v110
	v_fma_f32 v45, v34, v45, v111
	ds_read_b128 v[70:73], v47 offset:768
	ds_read_b128 v[74:77], v47 offset:784
	ds_read_b128 v[78:81], v47 offset:800
	ds_read_b128 v[82:85], v47 offset:816
	s_waitcnt lgkmcnt(4)
	v_mul_f32_e32 v102, v12, v86
	v_mul_f32_e32 v103, v13, v86
	v_mul_f32_e32 v104, v4, v90
	v_mul_f32_e32 v105, v5, v90
	v_mul_f32_e32 v106, v28, v94
	v_mul_f32_e32 v107, v29, v94
	v_mul_f32_e32 v108, v20, v98
	v_mul_f32_e32 v109, v21, v98
	v_fmac_f32_e32 v102, v14, v87
	v_fmac_f32_e32 v103, v15, v87
	v_fmac_f32_e32 v104, v6, v91
	v_fmac_f32_e32 v105, v7, v91
	v_fmac_f32_e32 v106, v30, v95
	v_fmac_f32_e32 v107, v31, v95
	v_fmac_f32_e32 v108, v22, v99
	v_fmac_f32_e32 v109, v23, v99
	v_fmac_f32_e32 v102, v8, v88
	v_fmac_f32_e32 v103, v9, v88
	v_fmac_f32_e32 v104, v0, v92
	v_fmac_f32_e32 v105, v1, v92
	v_fmac_f32_e32 v106, v24, v96
	v_fmac_f32_e32 v107, v25, v96
	v_fmac_f32_e32 v108, v16, v100
	v_fmac_f32_e32 v109, v17, v100
	v_fmac_f32_e32 v102, v10, v89
	v_fmac_f32_e32 v103, v11, v89
	v_fmac_f32_e32 v104, v2, v93
	v_fmac_f32_e32 v105, v3, v93
	v_fmac_f32_e32 v106, v26, v97
	v_fmac_f32_e32 v107, v27, v97
	v_fmac_f32_e32 v108, v18, v101
	v_fmac_f32_e32 v109, v19, v101
	v_add_f32_e32 v102, v102, v104
	v_add_f32_e32 v103, v103, v105
	v_add_f32_e32 v106, v106, v108
	v_add_f32_e32 v107, v107, v109
	v_add_f32_e32 v102, v102, v106
	v_add_f32_e32 v103, v103, v107
	v_fma_f32 v110, -v35, v45, v102
	v_fma_f32 v111, v35, v44, v103
	v_fma_f32 v44, v34, v44, v110
	v_fma_f32 v45, v34, v45, v111
	ds_read_b128 v[86:89], v47 offset:832
	ds_read_b128 v[90:93], v47 offset:848
	ds_read_b128 v[94:97], v47 offset:864
	ds_read_b128 v[98:101], v47 offset:880
	s_waitcnt lgkmcnt(4)
; template <bool FULL>
; DI void ssm_item(const P& p, int l, int item, char* smem) {
;     ...
;     for (int t = 0; t < 16; ++t) {
;       const float4* up = (const float4*)(us + t * 16);
;       const float4 u0 = up[0], u1 = up[1], u2 = up[2], u3 = up[3];
;       const float uu[16] = {u0.x, u0.y, u0.z, u0.w, u1.x, u1.y, u1.z, u1.w, u2.x, u2.y, u2.z, u2.w, u3.x, u3.y, u3.z, u3.w};
;       float br = 0.f, bi = 0.f;
; #pragma unroll
;       for (int i = 0; i < 16; ++i) { br = fmaf(bbr[i], uu[i], br); bi = fmaf(bbi[i], uu[i], bi); }
;       const float nhr = ar * hr - ai * hi + br, nhi = ar * hi + ai * hr + bi;
;       hr = nhr; hi = nhi;
;     ...
;   if (!FULL) p.E[((size_t)(b * 32 + g) * 64 + c) * 64 + lane] = make_float2(hr, hi);
	v_mul_f32_e32 v102, v12, v70
	v_mul_f32_e32 v103, v13, v70
	v_mul_f32_e32 v104, v4, v74
	v_mul_f32_e32 v105, v5, v74
	v_mul_f32_e32 v106, v28, v78
	v_mul_f32_e32 v107, v29, v78
	v_mul_f32_e32 v108, v20, v82
	v_mul_f32_e32 v109, v21, v82
	v_fmac_f32_e32 v102, v14, v71
	v_fmac_f32_e32 v103, v15, v71
	v_fmac_f32_e32 v104, v6, v75
	v_fmac_f32_e32 v105, v7, v75
	v_fmac_f32_e32 v106, v30, v79
	v_fmac_f32_e32 v107, v31, v79
	v_fmac_f32_e32 v108, v22, v83
	v_fmac_f32_e32 v109, v23, v83
	v_fmac_f32_e32 v102, v8, v72
	v_fmac_f32_e32 v103, v9, v72
	v_fmac_f32_e32 v104, v0, v76
	v_fmac_f32_e32 v105, v1, v76
	v_fmac_f32_e32 v106, v24, v80
	v_fmac_f32_e32 v107, v25, v80
	v_fmac_f32_e32 v108, v16, v84
	v_fmac_f32_e32 v109, v17, v84
	v_fmac_f32_e32 v102, v10, v73
	v_fmac_f32_e32 v103, v11, v73
	v_fmac_f32_e32 v104, v2, v77
	v_fmac_f32_e32 v105, v3, v77
	v_fmac_f32_e32 v106, v26, v81
	v_fmac_f32_e32 v107, v27, v81
	v_fmac_f32_e32 v108, v18, v85
	v_fmac_f32_e32 v109, v19, v85
	v_add_f32_e32 v102, v102, v104
	v_add_f32_e32 v103, v103, v105
	v_add_f32_e32 v106, v106, v108
	v_add_f32_e32 v107, v107, v109
	v_add_f32_e32 v102, v102, v106
	v_add_f32_e32 v103, v103, v107
	v_fma_f32 v110, -v35, v45, v102
	v_fma_f32 v111, v35, v44, v103
	v_fma_f32 v44, v34, v44, v110
	v_fma_f32 v45, v34, v45, v111
	ds_read_b128 v[70:73], v47 offset:896
	ds_read_b128 v[74:77], v47 offset:912
	ds_read_b128 v[78:81], v47 offset:928
	ds_read_b128 v[82:85], v47 offset:944
	s_waitcnt lgkmcnt(4)
	v_mul_f32_e32 v102, v12, v86
	v_mul_f32_e32 v103, v13, v86
	v_mul_f32_e32 v104, v4, v90
	v_mul_f32_e32 v105, v5, v90
	v_mul_f32_e32 v106, v28, v94
	v_mul_f32_e32 v107, v29, v94
	v_mul_f32_e32 v108, v20, v98
	v_mul_f32_e32 v109, v21, v98
	v_fmac_f32_e32 v102, v14, v87
	v_fmac_f32_e32 v103, v15, v87
	v_fmac_f32_e32 v104, v6, v91
	v_fmac_f32_e32 v105, v7, v91
	v_fmac_f32_e32 v106, v30, v95
	v_fmac_f32_e32 v107, v31, v95
	v_fmac_f32_e32 v108, v22, v99
	v_fmac_f32_e32 v109, v23, v99
	v_fmac_f32_e32 v102, v8, v88
	v_fmac_f32_e32 v103, v9, v88
	v_fmac_f32_e32 v104, v0, v92
	v_fmac_f32_e32 v105, v1, v92
	v_fmac_f32_e32 v106, v24, v96
	v_fmac_f32_e32 v107, v25, v96
	v_fmac_f32_e32 v108, v16, v100
	v_fmac_f32_e32 v109, v17, v100
	v_fmac_f32_e32 v102, v10, v89
	v_fmac_f32_e32 v103, v11, v89
	v_fmac_f32_e32 v104, v2, v93
	v_fmac_f32_e32 v105, v3, v93
	v_fmac_f32_e32 v106, v26, v97
	v_fmac_f32_e32 v107, v27, v97
	v_fmac_f32_e32 v108, v18, v101
	v_fmac_f32_e32 v109, v19, v101
	v_add_f32_e32 v102, v102, v104
	v_add_f32_e32 v103, v103, v105
	v_add_f32_e32 v106, v106, v108
	v_add_f32_e32 v107, v107, v109
	v_add_f32_e32 v102, v102, v106
	v_add_f32_e32 v103, v103, v107
	v_fma_f32 v110, -v35, v45, v102
	v_fma_f32 v111, v35, v44, v103
	v_fma_f32 v44, v34, v44, v110
	v_fma_f32 v45, v34, v45, v111
	ds_read_b128 v[86:89], v47 offset:960
	ds_read_b128 v[90:93], v47 offset:976
	ds_read_b128 v[94:97], v47 offset:992
	ds_read_b128 v[98:101], v47 offset:1008
	s_waitcnt lgkmcnt(4)
	v_mul_f32_e32 v102, v12, v70
	v_mul_f32_e32 v103, v13, v70
	v_mul_f32_e32 v104, v4, v74
	v_mul_f32_e32 v105, v5, v74
	v_mul_f32_e32 v106, v28, v78
	v_mul_f32_e32 v107, v29, v78
	v_mul_f32_e32 v108, v20, v82
	v_mul_f32_e32 v109, v21, v82
	v_fmac_f32_e32 v102, v14, v71
	v_fmac_f32_e32 v103, v15, v71
	v_fmac_f32_e32 v104, v6, v75
	v_fmac_f32_e32 v105, v7, v75
	v_fmac_f32_e32 v106, v30, v79
	v_fmac_f32_e32 v107, v31, v79
	v_fmac_f32_e32 v108, v22, v83
	v_fmac_f32_e32 v109, v23, v83
	v_fmac_f32_e32 v102, v8, v72
	v_fmac_f32_e32 v103, v9, v72
	v_fmac_f32_e32 v104, v0, v76
	v_fmac_f32_e32 v105, v1, v76
	v_fmac_f32_e32 v106, v24, v80
	v_fmac_f32_e32 v107, v25, v80
	v_fmac_f32_e32 v108, v16, v84
	v_fmac_f32_e32 v109, v17, v84
	v_fmac_f32_e32 v102, v10, v73
	v_fmac_f32_e32 v103, v11, v73
	v_fmac_f32_e32 v104, v2, v77
	v_fmac_f32_e32 v105, v3, v77
	v_fmac_f32_e32 v106, v26, v81
	v_fmac_f32_e32 v107, v27, v81
	v_fmac_f32_e32 v108, v18, v85
	v_fmac_f32_e32 v109, v19, v85
	v_add_f32_e32 v102, v102, v104
	v_add_f32_e32 v103, v103, v105
	v_add_f32_e32 v106, v106, v108
	v_add_f32_e32 v107, v107, v109
	v_add_f32_e32 v102, v102, v106
	v_add_f32_e32 v103, v103, v107
	v_fma_f32 v110, -v35, v45, v102
	v_fma_f32 v111, v35, v44, v103
	v_fma_f32 v44, v34, v44, v110
	v_fma_f32 v45, v34, v45, v111
	s_waitcnt lgkmcnt(0)
	v_mul_f32_e32 v102, v12, v86
	v_mul_f32_e32 v103, v13, v86
	v_mul_f32_e32 v104, v4, v90
	v_mul_f32_e32 v105, v5, v90
	v_mul_f32_e32 v106, v28, v94
	v_mul_f32_e32 v107, v29, v94
	v_mul_f32_e32 v108, v20, v98
	v_mul_f32_e32 v109, v21, v98
	v_fmac_f32_e32 v102, v14, v87
	v_fmac_f32_e32 v103, v15, v87
	v_fmac_f32_e32 v104, v6, v91
	v_fmac_f32_e32 v105, v7, v91
	v_fmac_f32_e32 v106, v30, v95
	v_fmac_f32_e32 v107, v31, v95
	v_fmac_f32_e32 v108, v22, v99
	v_fmac_f32_e32 v109, v23, v99
	v_fmac_f32_e32 v102, v8, v88
	v_fmac_f32_e32 v103, v9, v88
	v_fmac_f32_e32 v104, v0, v92
	v_fmac_f32_e32 v105, v1, v92
	v_fmac_f32_e32 v106, v24, v96
	v_fmac_f32_e32 v107, v25, v96
	v_fmac_f32_e32 v108, v16, v100
	v_fmac_f32_e32 v109, v17, v100
	v_fmac_f32_e32 v102, v10, v89
	v_fmac_f32_e32 v103, v11, v89
	v_fmac_f32_e32 v104, v2, v93
	v_fmac_f32_e32 v105, v3, v93
	v_fmac_f32_e32 v106, v26, v97
	v_fmac_f32_e32 v107, v27, v97
	v_fmac_f32_e32 v108, v18, v101
	v_fmac_f32_e32 v109, v19, v101
	v_add_f32_e32 v102, v102, v104
	v_add_f32_e32 v103, v103, v105
	v_add_f32_e32 v106, v106, v108
	v_add_f32_e32 v107, v107, v109
	v_add_f32_e32 v102, v102, v106
	v_add_f32_e32 v103, v103, v107
	v_fma_f32 v110, -v35, v45, v102
	v_fma_f32 v111, v35, v44, v103
	v_fma_f32 v44, v34, v44, v110
	v_fma_f32 v45, v34, v45, v111
	s_cmp_eq_u32 s1, 8
	s_cbranch_scc0 .LBB0_355
	v_lshl_add_u32 v0, s0, 5, v33
	v_ashrrev_i32_e32 v1, 31, v0
	v_lshlrev_b64 v[0:1], 15, v[0:1]
	v_lshl_add_u64 v[0:1], s[82:83], 0, v[0:1]
	s_lshl_b32 s60, s5, 9
	v_readlane_b32 s0, v249, 5
	v_lshl_add_u64 v[0:1], v[0:1], 0, s[60:61]
	v_lshlrev_b32_e32 v192, 3, v32
	s_add_i32 s4, s4, s0
	v_lshl_add_u64 v[0:1], v[0:1], 0, v[192:193]
	s_cmpk_gt_i32 s4, 0xfff
	v_readlane_b32 s1, v249, 6
	global_store_dwordx2 v[0:1], v[44:45], off
	s_cbranch_scc0 .LBB0_354
